# P0 weight-conversion stores marked nt (converted weights are consumed phases later)
# baseline (speedup 1.0000x reference)
; #define LAS __attribute__((address_space(3)))
; __device__ __forceinline__ void tr_block8(const float* src, int ldw, unsigned char* dst  , int Kb, float sc, LAS float* scr, int lane) {
;     const int kr = lane >> 3, c4 = lane & 7;
;     f32x4 v[8];
; #pragma unroll
;     for (int i = 0; i < 8; ++i) v[i] = *(const f32x4*)(src + (size_t)(8 * i + kr) * ldw + 4 * c4);
; #pragma unroll
;     for (int i = 0; i < 8; ++i) { LAS float* d = scr + (8 * i + kr) * 33 + 4 * c4; d[0] = v[i].x; d[1] = v[i].y; d[2] = v[i].z; d[3] = v[i].w; }
;     asm volatile("s_waitcnt lgkmcnt(0)" ::: "memory");
;     const int c = lane & 7;
; #pragma unroll
;     for (int j = 0; j < 4; ++j) { const int n = (lane >> 3) + 8 * j; const LAS float* s = scr + (8 * c) * 33 + n;
;         int w0 = 0, w1 = 0; w0 = __builtin_amdgcn_cvt_pk_fp8_f32(s[0 * 33] * sc, s[1 * 33] * sc, w0, false); w0 = __builtin_amdgcn_cvt_pk_fp8_f32(s[2 * 33] * sc, s[3 * 33] * sc, w0, true);
;         w1 = __builtin_amdgcn_cvt_pk_fp8_f32(s[4 * 33] * sc, s[5 * 33] * sc, w1, false); w1 = __builtin_amdgcn_cvt_pk_fp8_f32(s[6 * 33] * sc, s[7 * 33] * sc, w1, true);
;         *(v2u*)(dst + (size_t)n * Kb + 8 * c) = (v2u){(unsigned)w0, (unsigned)w1}; }
;     asm volatile("s_waitcnt lgkmcnt(0)" ::: "memory");
; }
; template <int SEL> __global__ void __launch_bounds__(NWAVES * 64, 2) fwd_kernel(Args args) {
;     ...
;             r -= 2 * I_L;
;             if (r < I_GU) { if constexpr (DENSE_FP8 != 0) tr_seg8<1>(in[16], 2 * DFF, 1024, 0, 2 * DFF, (unsigned char*)q_Wgu_t, 0, DFF, W8_SCALE, scr, r, lane); else tr_seg<1>(in[16], 2 * DFF, 1024, 0, 2 * DFF, q_Wgu_t, 0, DFF, scr, r, lane); continue; } r -= I_GU;
;             if (r < I_DN) { if constexpr (DENSE_FP8 == 2) tr_seg8<0>(in[17], 1024, DFF, 0, 1024, (unsigned char*)q_Wdn_t, 0, 0, W8_SCALE, scr, r, lane); else tr_seg<0>(in[17], 1024, DFF, 0, 1024, q_Wdn_t, 0, 0, scr, r, lane); continue; } r -= I_DN;
;             if (r < 8 * I_EGU) { const int e = r / I_EGU; r -= e * I_EGU; tr_seg8<1>(in[19] + (size_t)e * 1024 * 2 * DFFE, 2 * DFFE, 1024, 0, 2 * DFFE, (unsigned char*)q_Wegu_t + (size_t)e * 2 * DFFE * 1024, 0, DFFE, W8_SCALE, scr, r, lane); continue; } r -= 8 * I_EGU;
;             { const int e = r / I_EDN; r -= e * I_EDN; tr_seg8<0>(in[20] + (size_t)e * DFFE * 1024, 1024, DFFE, 0, 1024, (unsigned char*)q_Wedn_t + (size_t)e * 1024 * DFFE, 0, 0, W8_SCALE, scr, r, lane); }
.LBB0_10:
	s_add_i32 s4, s3, 0x9c80
	s_cmpk_gt_i32 s4, 0x1bff
	s_mov_b64 s[18:19], -1
	s_cbranch_scc0 .LBB0_24
	s_cmpk_gt_u32 s4, 0x26ff
	s_cbranch_scc0 .LBB0_21
	s_cmpk_gt_u32 s4, 0x2c7f
	s_cbranch_scc0 .LBB0_18
	s_cmpk_gt_u32 s4, 0x9c7f
	s_cbranch_scc0 .LBB0_15
	s_and_b32 s18, s3, 0xffff
	s_mul_hi_u32 s18, s18, 0x24924a
	s_bfe_u32 s19, s3, 0x80008
	s_mul_i32 s18, s18, 0xf900
	s_mulk_i32 s19, 0x2493
	s_lshr_b32 s52, s19, 16
	s_add_i32 s53, s3, s18
	s_mov_b64 s[18:19], s[0:1]
	s_load_dwordx2 s[18:19], s[18:19], 0xa0
	s_mov_b64 s[20:21], s[0:1]
	s_load_dwordx2 s[20:21], s[20:21], 0xc0
	s_mul_i32 s54, s52, 0xe00000
	s_waitcnt lgkmcnt(0)
	s_add_u32 s54, s18, s54
	s_addc_u32 s55, s19, 0
	s_mul_i32 s52, s52, 0x380000
	s_add_u32 s56, s20, s52
	s_sext_i32_i16 s18, s53
	s_addc_u32 s57, s21, 0
	s_bfe_u32 s18, s18, 0x5001a
	s_add_i32 s18, s53, s18
	s_sext_i32_i16 s19, s18
	s_and_b32 s18, s18, 0xffe0
	s_sub_i32 s18, s53, s18
	s_sext_i32_i16 s58, s18
	s_lshl_b32 s18, s19, 1
	s_andn2_b32 s18, s18, 63
	s_ashr_i32 s19, s18, 31
	s_lshl_b32 s20, s58, 5
	s_lshl_b64 s[52:53], s[18:19], 12
	s_add_u32 s54, s54, s52
	s_addc_u32 s55, s55, s53
	s_ashr_i32 s21, s20, 31
	s_lshl_b64 s[52:53], s[20:21], 2
	s_add_u32 s52, s54, s52
	s_addc_u32 s53, s55, s53
	v_lshl_add_u64 v[92:93], s[52:53], 0, v[2:3]
	v_mov_b32_e32 v59, v3
	v_mov_b32_e32 v61, v3
	v_mov_b32_e32 v63, v3
	v_lshlrev_b32_e32 v74, 2, v10
	v_mov_b32_e32 v75, v3
	v_lshlrev_b32_e32 v80, 2, v12
	v_mov_b32_e32 v81, v3
	v_lshlrev_b32_e32 v82, 2, v14
	v_mov_b32_e32 v83, v3
	v_lshl_add_u64 v[64:65], v[92:93], 0, v[58:59]
	v_lshl_add_u64 v[68:69], v[92:93], 0, v[60:61]
	v_lshl_add_u64 v[72:73], v[92:93], 0, v[62:63]
	v_lshl_add_u64 v[76:77], v[92:93], 0, v[74:75]
	v_lshl_add_u64 v[80:81], v[92:93], 0, v[80:81]
	v_lshl_add_u64 v[84:85], v[92:93], 0, v[82:83]
	global_load_dwordx4 v[64:67], v[64:65], off nt
	s_nop 0
	global_load_dwordx4 v[68:71], v[68:69], off nt
	s_nop 0
	global_load_dwordx4 v[72:75], v[72:73], off nt
	s_nop 0
	global_load_dwordx4 v[76:79], v[76:77], off nt
	s_nop 0
	global_load_dwordx4 v[80:83], v[80:81], off nt
	s_nop 0
	global_load_dwordx4 v[84:87], v[84:85], off nt
	v_lshlrev_b32_e32 v88, 2, v16
	v_mov_b32_e32 v89, v3
	v_lshl_add_u64 v[88:89], v[92:93], 0, v[88:89]
	global_load_dwordx4 v[88:91], v[88:89], off nt
	v_lshlrev_b32_e32 v94, 2, v18
	v_mov_b32_e32 v95, v3
	v_lshl_add_u64 v[92:93], v[92:93], 0, v[94:95]
	global_load_dwordx4 v[92:95], v[92:93], off nt
	v_add_u32_e32 v19, v13, v15
	v_add_u32_e32 v27, 0x420, v19
	v_add_u32_e32 v29, 0x428, v19
	v_add_u32_e32 v31, 0x840, v19
	v_add_u32_e32 v33, 0x848, v19
	v_add_u32_e32 v35, 0xc60, v19
	v_add_u32_e32 v37, 0xc68, v19
	v_add_u32_e32 v39, 0x1080, v19
	v_add_u32_e32 v41, 0x1088, v19
	v_add_u32_e32 v43, 0x14a0, v19
	v_add_u32_e32 v45, 0x14a8, v19
	v_add_u32_e32 v47, 0x18c0, v19
	v_add_u32_e32 v49, 0x18c8, v19
	v_add_u32_e32 v51, 0x1ce0, v19
	v_add_u32_e32 v53, 0x1ce8, v19
	v_mov_b32_e32 v96, v3
	v_mov_b32_e32 v97, v3
	s_mul_i32 s58, s58, 0x1c000
	s_mul_hi_i32 s20, s20, 0xe00
	s_add_u32 s21, s56, s58
	s_addc_u32 s20, s57, s20
	s_add_u32 s18, s21, s18
	s_addc_u32 s19, s20, s19
	s_waitcnt vmcnt(7)
	ds_write2_b32 v19, v64, v65 offset1:1
	ds_write2_b32 v19, v66, v67 offset0:2 offset1:3
	s_waitcnt vmcnt(6)
	ds_write2_b32 v27, v68, v69 offset1:1
	ds_write2_b32 v29, v70, v71 offset1:1
	s_waitcnt vmcnt(5)
	ds_write2_b32 v31, v72, v73 offset1:1
	ds_write2_b32 v33, v74, v75 offset1:1
	s_waitcnt vmcnt(4)
	ds_write2_b32 v35, v76, v77 offset1:1
	ds_write2_b32 v37, v78, v79 offset1:1
	s_waitcnt vmcnt(3)
	ds_write2_b32 v39, v80, v81 offset1:1
	ds_write2_b32 v41, v82, v83 offset1:1
	s_waitcnt vmcnt(2)
	ds_write2_b32 v43, v84, v85 offset1:1
	ds_write2_b32 v45, v86, v87 offset1:1
	s_waitcnt vmcnt(1)
	ds_write2_b32 v47, v88, v89 offset1:1
	ds_write2_b32 v49, v90, v91 offset1:1
	s_waitcnt vmcnt(0)
	ds_write2_b32 v51, v92, v93 offset1:1
	ds_write2_b32 v53, v94, v95 offset1:1
	s_waitcnt lgkmcnt(0)
	ds_read2_b32 v[64:65], v17 offset1:8
	ds_read2_b32 v[66:67], v17 offset0:33 offset1:41
	ds_read2_b32 v[70:71], v17 offset0:66 offset1:74
	ds_read2_b32 v[72:73], v17 offset0:99 offset1:107
	ds_read2_b32 v[74:75], v17 offset0:132 offset1:140
	ds_read2_b32 v[76:77], v17 offset0:165 offset1:173
	ds_read2_b32 v[78:79], v17 offset0:198 offset1:206
	ds_read2_b32 v[80:81], v17 offset0:231 offset1:239
	s_waitcnt lgkmcnt(7)
	v_mul_f32_e32 v19, 0x42800000, v64
	s_waitcnt lgkmcnt(6)
	v_mul_f32_e32 v27, 0x42800000, v66
	v_cvt_pk_fp8_f32 v96, v19, v27
	s_waitcnt lgkmcnt(3)
	v_mul_f32_e32 v29, 0x42800000, v74
	s_waitcnt lgkmcnt(2)
	v_mul_f32_e32 v31, 0x42800000, v76
	v_cvt_pk_fp8_f32 v97, v29, v31
	v_mul_f32_e32 v19, 0x42800000, v70
	v_mul_f32_e32 v27, 0x42800000, v72
	v_cvt_pk_fp8_f32 v96, v19, v27 op_sel:[0,0,1]
	s_waitcnt lgkmcnt(1)
	v_mul_f32_e32 v19, 0x42800000, v78
	s_waitcnt lgkmcnt(0)
	v_mul_f32_e32 v27, 0x42800000, v80
	v_cvt_pk_fp8_f32 v97, v19, v27 op_sel:[0,0,1]
	v_mul_f32_e32 v19, 0x42800000, v65
	v_mul_f32_e32 v27, 0x42800000, v67
	v_mov_b32_e32 v64, v3
	v_cvt_pk_fp8_f32 v64, v19, v27
	v_mul_f32_e32 v29, 0x42800000, v75
	v_mul_f32_e32 v31, 0x42800000, v77
	v_mov_b32_e32 v65, v3
	v_cvt_pk_fp8_f32 v65, v29, v31
	v_lshl_add_u64 v[68:69], s[18:19], 0, v[20:21]
	v_mul_f32_e32 v19, 0x42800000, v71
	v_mul_f32_e32 v27, 0x42800000, v73
	v_lshl_add_u64 v[68:69], v[68:69], 0, v[22:23]
	v_cvt_pk_fp8_f32 v64, v19, v27 op_sel:[0,0,1]
	v_mul_f32_e32 v19, 0x42800000, v79
	v_mul_f32_e32 v27, 0x42800000, v81
	v_add_co_u32_e32 v82, vcc, s29, v68
	v_cvt_pk_fp8_f32 v65, v19, v27 op_sel:[0,0,1]
	s_nop 0
	v_addc_co_u32_e32 v83, vcc, 0, v69, vcc
	v_add_co_u32_e32 v72, vcc, s31, v68
	global_store_dwordx2 v[82:83], v[96:97], off nt
	s_nop 0
	v_addc_co_u32_e32 v73, vcc, 0, v69, vcc
	ds_read2_b32 v[66:67], v17 offset0:16 offset1:24
	ds_read2_b32 v[70:71], v17 offset0:49 offset1:57
	global_store_dwordx2 v[72:73], v[64:65], off nt
	ds_read2_b32 v[72:73], v17 offset0:82 offset1:90
	ds_read2_b32 v[74:75], v17 offset0:115 offset1:123
	ds_read2_b32 v[76:77], v17 offset0:148 offset1:156
	ds_read2_b32 v[78:79], v17 offset0:181 offset1:189
	v_mov_b32_e32 v64, v3
	s_waitcnt lgkmcnt(5)
; #define in KArgIn()
; __device__ __forceinline__ void tr_block8(const float* src, int ldw, unsigned char* dst  , int Kb, float sc, LAS float* scr, int lane) {
;     const int kr = lane >> 3, c4 = lane & 7;
;     f32x4 v[8];
; #pragma unroll
;     for (int i = 0; i < 8; ++i) v[i] = *(const f32x4*)(src + (size_t)(8 * i + kr) * ldw + 4 * c4);
; #pragma unroll
;     for (int i = 0; i < 8; ++i) { LAS float* d = scr + (8 * i + kr) * 33 + 4 * c4; d[0] = v[i].x; d[1] = v[i].y; d[2] = v[i].z; d[3] = v[i].w; }
;     asm volatile("s_waitcnt lgkmcnt(0)" ::: "memory");
;     const int c = lane & 7;
; #pragma unroll
;     for (int j = 0; j < 4; ++j) { const int n = (lane >> 3) + 8 * j; const LAS float* s = scr + (8 * c) * 33 + n;
;         int w0 = 0, w1 = 0; w0 = __builtin_amdgcn_cvt_pk_fp8_f32(s[0 * 33] * sc, s[1 * 33] * sc, w0, false); w0 = __builtin_amdgcn_cvt_pk_fp8_f32(s[2 * 33] * sc, s[3 * 33] * sc, w0, true);
;         w1 = __builtin_amdgcn_cvt_pk_fp8_f32(s[4 * 33] * sc, s[5 * 33] * sc, w1, false); w1 = __builtin_amdgcn_cvt_pk_fp8_f32(s[6 * 33] * sc, s[7 * 33] * sc, w1, true);
;         *(v2u*)(dst + (size_t)n * Kb + 8 * c) = (v2u){(unsigned)w0, (unsigned)w1}; }
;     asm volatile("s_waitcnt lgkmcnt(0)" ::: "memory");
; }
; template <int MAP> __device__ __forceinline__ void tr_seg8(const float* W, int ldw, int K, int c0, int ncols, unsigned char* WT, int row_off, int F, float sc, LAS float* scr, int item, int lane) {
;     const int nblk = ncols / 32, kb = item / nblk, nb = item % nblk, k0 = 64 * kb, n0 = 32 * nb;
;     int drow;
;     if (MAP == 0) drow = row_off + n0; else { int c = n0; const int up = c >= F; if (up) c -= F; drow = row_off + 256 * (c / 128) + 128 * up + (c % 128); }
;     tr_block8(W + (size_t)k0 * ldw + c0 + n0, ldw, WT + (size_t)drow * K + k0, K, sc, scr, lane);
; }
; template <int SEL> __global__ void __launch_bounds__(NWAVES * 64, 2) fwd_kernel(Args args) {
;     ...
;             if (r < 8 * I_EGU) { const int e = r / I_EGU; r -= e * I_EGU; tr_seg8<1>(in[19] + (size_t)e * 1024 * 2 * DFFE, 2 * DFFE, 1024, 0, 2 * DFFE, (unsigned char*)q_Wegu_t + (size_t)e * 2 * DFFE * 1024, 0, DFFE, W8_SCALE, scr, r, lane); continue; } r -= 8 * I_EGU;
;             { const int e = r / I_EDN; r -= e * I_EDN; tr_seg8<0>(in[20] + (size_t)e * DFFE * 1024, 1024, DFFE, 0, 1024, (unsigned char*)q_Wedn_t + (size_t)e * 1024 * DFFE, 0, 0, W8_SCALE, scr, r, lane); }
	v_mul_f32_e32 v19, 0x42800000, v66
	s_waitcnt lgkmcnt(4)
	v_mul_f32_e32 v27, 0x42800000, v70
	ds_read2_b32 v[80:81], v17 offset0:214 offset1:222
	ds_read2_b32 v[82:83], v17 offset0:247 offset1:255
	v_cvt_pk_fp8_f32 v64, v19, v27
	s_waitcnt lgkmcnt(3)
	v_mul_f32_e32 v29, 0x42800000, v76
	s_waitcnt lgkmcnt(2)
	v_mul_f32_e32 v31, 0x42800000, v78
	v_mov_b32_e32 v65, v3
	v_cvt_pk_fp8_f32 v65, v29, v31
	v_mul_f32_e32 v19, 0x42800000, v72
	v_mul_f32_e32 v27, 0x42800000, v74
	v_cvt_pk_fp8_f32 v64, v19, v27 op_sel:[0,0,1]
	s_waitcnt lgkmcnt(1)
	v_mul_f32_e32 v19, 0x42800000, v80
	s_waitcnt lgkmcnt(0)
	v_mul_f32_e32 v27, 0x42800000, v82
	v_cvt_pk_fp8_f32 v65, v19, v27 op_sel:[0,0,1]
	v_add_co_u32_e32 v84, vcc, s34, v68
	v_mul_f32_e32 v19, 0x42800000, v67
	s_nop 0
	v_addc_co_u32_e32 v85, vcc, 0, v69, vcc
	global_store_dwordx2 v[84:85], v[64:65], off nt
	v_mul_f32_e32 v27, 0x42800000, v71
	v_mov_b32_e32 v64, v3
	v_cvt_pk_fp8_f32 v64, v19, v27
	v_mul_f32_e32 v29, 0x42800000, v77
	v_mul_f32_e32 v31, 0x42800000, v79
	v_mov_b32_e32 v65, v3
	v_cvt_pk_fp8_f32 v65, v29, v31
	v_mul_f32_e32 v19, 0x42800000, v73
	v_mul_f32_e32 v27, 0x42800000, v75
	v_cvt_pk_fp8_f32 v64, v19, v27 op_sel:[0,0,1]
	v_mul_f32_e32 v19, 0x42800000, v81
	v_mul_f32_e32 v27, 0x42800000, v83
	v_cvt_pk_fp8_f32 v65, v19, v27 op_sel:[0,0,1]
	v_add_co_u32_e32 v66, vcc, 0xad15000, v68
	s_mov_b64 s[18:19], 0
	s_nop 0
	v_addc_co_u32_e32 v67, vcc, 0, v69, vcc
	global_store_dwordx2 v[66:67], v[64:65], off nt
	s_waitcnt lgkmcnt(0)
.LBB0_15:
	s_andn2_b64 vcc, exec, s[18:19]
	s_cbranch_vccnz .LBB0_17
	s_and_b32 s18, 0xffff, s22
	s_mul_hi_u32 s18, s18, 0x124925
	s_mul_i32 s18, s18, 0xf200
	s_add_i32 s19, s3, 0x7000
	s_bfe_u32 s20, s19, 0x100009
	s_add_i32 s53, s19, s18
	s_mov_b64 s[18:19], s[0:1]
	s_mulk_i32 s20, 0x2493
	s_lshr_b32 s52, s20, 16
	s_load_dwordx2 s[18:19], s[18:19], 0x98
	s_mov_b64 s[20:21], s[0:1]
	s_load_dwordx2 s[20:21], s[20:21], 0xc0
	s_mul_i32 s54, s52, 0x1c00000
	s_waitcnt lgkmcnt(0)
	s_add_u32 s54, s18, s54
	s_addc_u32 s19, s19, 0
	s_mul_i32 s52, s52, 0x700000
	s_sext_i32_i16 s18, s53
	s_add_u32 s52, s20, s52
	s_mulk_i32 s18, 0x4925
	s_addc_u32 s55, s21, 0
	s_lshr_b32 s20, s18, 31
	s_ashr_i32 s18, s18, 22
	s_add_i32 s21, s18, s20
	s_mul_i32 s18, s21, 0xe0
	s_sub_i32 s18, s53, s18
	s_sext_i32_i16 s20, s18
	s_lshl_b32 s18, s20, 5
	s_cmpk_lt_i32 s20, 0x70
	s_cselect_b32 s53, 0, 0xf200
	s_cselect_b32 s20, 0, 0x80
	s_add_i32 s53, s53, s18
	s_sext_i32_i16 s57, s53
	s_bfe_u32 s57, s57, 0x70018
	s_add_i32 s57, s53, s57
	s_sext_i32_i16 s58, s57
	s_and_b32 s57, s57, 0xff80
	s_sub_i32 s53, s53, s57
	s_lshl_b32 s58, s58, 1
	s_sext_i32_i16 s53, s53
	s_lshl_b32 s56, s21, 6
	s_and_b32 s58, s58, 0xffffff00
	s_add_i32 s20, s20, s53
	s_add_i32 s20, s20, s58
	s_ashr_i32 s53, s56, 31
	s_mul_i32 s21, s21, 0x1c0000
	s_mul_hi_i32 s57, s56, 0x7000
	s_add_u32 s21, s54, s21
	s_addc_u32 s54, s19, s57
	s_ashr_i32 s19, s18, 31
	s_lshl_b64 s[18:19], s[18:19], 2
	s_add_u32 s18, s21, s18
	s_addc_u32 s19, s54, s19
	v_lshl_add_u64 v[92:93], s[18:19], 0, v[2:3]
	v_mov_b32_e32 v43, v3
	v_lshl_add_u64 v[80:81], v[92:93], 0, v[42:43]
	v_add_co_u32_e32 v68, vcc, s35, v80
	v_mov_b32_e32 v45, v3
	s_nop 0
	v_addc_co_u32_e32 v69, vcc, 0, v81, vcc
	v_add_co_u32_e32 v72, vcc, s36, v80
	global_load_dwordx4 v[64:67], v[80:81], off nt
	s_nop 0
	global_load_dwordx4 v[68:71], v[68:69], off nt
	v_addc_co_u32_e32 v73, vcc, 0, v81, vcc
	v_add_co_u32_e32 v76, vcc, s37, v80
	v_lshl_add_u64 v[84:85], v[92:93], 0, v[44:45]
	s_nop 0
	v_addc_co_u32_e32 v77, vcc, 0, v81, vcc
	v_add_co_u32_e32 v80, vcc, s38, v80
	v_mov_b32_e32 v47, v3
	s_nop 0
	v_addc_co_u32_e32 v81, vcc, 0, v81, vcc
	global_load_dwordx4 v[72:75], v[72:73], off nt
	s_nop 0
	global_load_dwordx4 v[76:79], v[76:77], off nt
	s_nop 0
	global_load_dwordx4 v[80:83], v[80:81], off nt
	s_nop 0
	global_load_dwordx4 v[84:87], v[84:85], off nt
	v_lshl_add_u64 v[88:89], v[92:93], 0, v[46:47]
	v_mov_b32_e32 v49, v3
	global_load_dwordx4 v[88:91], v[88:89], off nt
	v_lshl_add_u64 v[92:93], v[92:93], 0, v[48:49]
	global_load_dwordx4 v[92:95], v[92:93], off nt
	v_add_u32_e32 v19, v13, v15
	v_add_u32_e32 v27, 0x420, v19
	v_add_u32_e32 v29, 0x428, v19
	v_add_u32_e32 v31, 0x840, v19
	v_add_u32_e32 v33, 0x848, v19
	v_add_u32_e32 v35, 0xc60, v19
	v_add_u32_e32 v37, 0xc68, v19
	v_add_u32_e32 v39, 0x1080, v19
	v_add_u32_e32 v41, 0x1088, v19
	v_add_u32_e32 v43, 0x14a0, v19
	v_add_u32_e32 v45, 0x14a8, v19
	v_add_u32_e32 v47, 0x18c0, v19
	s_ashr_i32 s21, s20, 31
	s_lshl_b64 s[18:19], s[20:21], 10
	s_add_u32 s18, s52, s18
	s_addc_u32 s19, s55, s19
	s_add_u32 s18, s18, s56
	s_addc_u32 s19, s19, s53
	s_waitcnt vmcnt(7)
; #define LAS __attribute__((address_space(3)))
; __device__ __forceinline__ void tr_block8(const float* src, int ldw, unsigned char* dst  , int Kb, float sc, LAS float* scr, int lane) {
;     const int kr = lane >> 3, c4 = lane & 7;
;     f32x4 v[8];
; #pragma unroll
;     for (int i = 0; i < 8; ++i) v[i] = *(const f32x4*)(src + (size_t)(8 * i + kr) * ldw + 4 * c4);
; #pragma unroll
;     for (int i = 0; i < 8; ++i) { LAS float* d = scr + (8 * i + kr) * 33 + 4 * c4; d[0] = v[i].x; d[1] = v[i].y; d[2] = v[i].z; d[3] = v[i].w; }
;     asm volatile("s_waitcnt lgkmcnt(0)" ::: "memory");
;     const int c = lane & 7;
; #pragma unroll
;     for (int j = 0; j < 4; ++j) { const int n = (lane >> 3) + 8 * j; const LAS float* s = scr + (8 * c) * 33 + n;
;         int w0 = 0, w1 = 0; w0 = __builtin_amdgcn_cvt_pk_fp8_f32(s[0 * 33] * sc, s[1 * 33] * sc, w0, false); w0 = __builtin_amdgcn_cvt_pk_fp8_f32(s[2 * 33] * sc, s[3 * 33] * sc, w0, true);
;         w1 = __builtin_amdgcn_cvt_pk_fp8_f32(s[4 * 33] * sc, s[5 * 33] * sc, w1, false); w1 = __builtin_amdgcn_cvt_pk_fp8_f32(s[6 * 33] * sc, s[7 * 33] * sc, w1, true);
;         *(v2u*)(dst + (size_t)n * Kb + 8 * c) = (v2u){(unsigned)w0, (unsigned)w1}; }
;     asm volatile("s_waitcnt lgkmcnt(0)" ::: "memory");
	ds_write2_b32 v19, v64, v65 offset1:1
	ds_write2_b32 v19, v66, v67 offset0:2 offset1:3
	s_waitcnt vmcnt(6)
	ds_write2_b32 v27, v68, v69 offset1:1
	ds_write2_b32 v29, v70, v71 offset1:1
	s_waitcnt vmcnt(5)
	ds_write2_b32 v31, v72, v73 offset1:1
	ds_write2_b32 v33, v74, v75 offset1:1
	s_waitcnt vmcnt(4)
	ds_write2_b32 v35, v76, v77 offset1:1
	ds_write2_b32 v37, v78, v79 offset1:1
	s_waitcnt vmcnt(3)
	ds_write2_b32 v39, v80, v81 offset1:1
	ds_write2_b32 v41, v82, v83 offset1:1
	s_waitcnt vmcnt(2)
	ds_write2_b32 v43, v84, v85 offset1:1
	ds_write2_b32 v45, v86, v87 offset1:1
	s_waitcnt vmcnt(1)
	ds_write2_b32 v47, v88, v89 offset1:1
	v_add_u32_e32 v27, 0x18c8, v19
	v_mov_b32_e32 v70, v3
	ds_write2_b32 v27, v90, v91 offset1:1
	v_add_u32_e32 v27, 0x1ce0, v19
	v_add_u32_e32 v19, 0x1ce8, v19
	s_waitcnt vmcnt(0)
	ds_write2_b32 v27, v92, v93 offset1:1
	ds_write2_b32 v19, v94, v95 offset1:1
	s_waitcnt lgkmcnt(0)
	ds_read2_b32 v[64:65], v17 offset1:8
	ds_read2_b32 v[66:67], v17 offset0:33 offset1:41
	ds_read2_b32 v[72:73], v17 offset0:66 offset1:74
	ds_read2_b32 v[74:75], v17 offset0:99 offset1:107
	ds_read2_b32 v[76:77], v17 offset0:132 offset1:140
	ds_read2_b32 v[78:79], v17 offset0:165 offset1:173
	ds_read2_b32 v[80:81], v17 offset0:198 offset1:206
	ds_read2_b32 v[82:83], v17 offset0:231 offset1:239
	v_mov_b32_e32 v71, v3
	s_waitcnt lgkmcnt(7)
	v_mul_f32_e32 v19, 0x42800000, v64
	s_waitcnt lgkmcnt(6)
	v_mul_f32_e32 v27, 0x42800000, v66
	v_cvt_pk_fp8_f32 v70, v19, v27
	s_waitcnt lgkmcnt(3)
	v_mul_f32_e32 v29, 0x42800000, v76
	s_waitcnt lgkmcnt(2)
	v_mul_f32_e32 v31, 0x42800000, v78
	v_cvt_pk_fp8_f32 v71, v29, v31
	v_mul_f32_e32 v19, 0x42800000, v72
	v_mul_f32_e32 v27, 0x42800000, v74
	v_cvt_pk_fp8_f32 v70, v19, v27 op_sel:[0,0,1]
	s_waitcnt lgkmcnt(1)
	v_mul_f32_e32 v19, 0x42800000, v80
	s_waitcnt lgkmcnt(0)
	v_mul_f32_e32 v27, 0x42800000, v82
	v_cvt_pk_fp8_f32 v71, v19, v27 op_sel:[0,0,1]
	v_mul_f32_e32 v19, 0x42800000, v65
	v_mul_f32_e32 v27, 0x42800000, v67
	v_mov_b32_e32 v64, v3
	v_cvt_pk_fp8_f32 v64, v19, v27
	v_mul_f32_e32 v29, 0x42800000, v77
	v_mul_f32_e32 v31, 0x42800000, v79
	v_mov_b32_e32 v65, v3
	v_cvt_pk_fp8_f32 v65, v29, v31
	v_mul_f32_e32 v19, 0x42800000, v73
	v_mul_f32_e32 v27, 0x42800000, v75
	v_cvt_pk_fp8_f32 v64, v19, v27 op_sel:[0,0,1]
	v_mul_f32_e32 v19, 0x42800000, v81
	v_mul_f32_e32 v27, 0x42800000, v83
	v_lshl_add_u64 v[68:69], s[18:19], 0, v[20:21]
	v_cvt_pk_fp8_f32 v65, v19, v27 op_sel:[0,0,1]
	v_lshl_add_u64 v[68:69], v[68:69], 0, s[6:7]
	v_lshl_add_u64 v[84:85], v[68:69], 0, v[4:5]
	ds_read2_b32 v[66:67], v17 offset0:16 offset1:24
	ds_read2_b32 v[72:73], v17 offset0:49 offset1:57
	global_store_dwordx2 v[84:85], v[70:71], off nt
	v_lshl_add_u64 v[70:71], v[68:69], 0, v[6:7]
	global_store_dwordx2 v[70:71], v[64:65], off nt
	ds_read2_b32 v[70:71], v17 offset0:82 offset1:90
	ds_read2_b32 v[74:75], v17 offset0:115 offset1:123
	ds_read2_b32 v[76:77], v17 offset0:148 offset1:156
	ds_read2_b32 v[78:79], v17 offset0:181 offset1:189
	s_waitcnt lgkmcnt(5)
	v_mul_f32_e32 v19, 0x42800000, v66
	s_waitcnt lgkmcnt(4)
	v_mul_f32_e32 v27, 0x42800000, v72
	v_mov_b32_e32 v64, v3
	ds_read2_b32 v[80:81], v17 offset0:214 offset1:222
	ds_read2_b32 v[82:83], v17 offset0:247 offset1:255
	v_cvt_pk_fp8_f32 v64, v19, v27
	s_waitcnt lgkmcnt(3)
	v_mul_f32_e32 v29, 0x42800000, v76
	s_waitcnt lgkmcnt(2)
	v_mul_f32_e32 v31, 0x42800000, v78
	v_mov_b32_e32 v65, v3
	v_cvt_pk_fp8_f32 v65, v29, v31
	v_mul_f32_e32 v19, 0x42800000, v70
	v_mul_f32_e32 v27, 0x42800000, v74
	v_cvt_pk_fp8_f32 v64, v19, v27 op_sel:[0,0,1]
	s_waitcnt lgkmcnt(1)
	v_mul_f32_e32 v19, 0x42800000, v80
	s_waitcnt lgkmcnt(0)
	v_mul_f32_e32 v27, 0x42800000, v82
	v_cvt_pk_fp8_f32 v65, v19, v27 op_sel:[0,0,1]
	v_mul_f32_e32 v19, 0x42800000, v67
	v_mul_f32_e32 v27, 0x42800000, v73
	v_mov_b32_e32 v66, v3
	v_cvt_pk_fp8_f32 v66, v19, v27
	v_mul_f32_e32 v29, 0x42800000, v77
	v_mul_f32_e32 v31, 0x42800000, v79
	v_mov_b32_e32 v67, v3
	v_cvt_pk_fp8_f32 v67, v29, v31
	v_mul_f32_e32 v19, 0x42800000, v71
	v_mul_f32_e32 v27, 0x42800000, v75
	v_cvt_pk_fp8_f32 v66, v19, v27 op_sel:[0,0,1]
	v_mul_f32_e32 v19, 0x42800000, v81
	v_mul_f32_e32 v27, 0x42800000, v83
	v_cvt_pk_fp8_f32 v67, v19, v27 op_sel:[0,0,1]
	v_lshl_add_u64 v[70:71], v[68:69], 0, v[8:9]
	global_store_dwordx2 v[70:71], v[64:65], off nt
	v_lshl_add_u64 v[64:65], v[68:69], 0, v[10:11]
	global_store_dwordx2 v[64:65], v[66:67], off nt
	s_waitcnt lgkmcnt(0)

; #define LAS __attribute__((address_space(3)))
; #define in KArgIn()
; __device__ __forceinline__ void tr_block8(const float* src, int ldw, unsigned char* dst  , int Kb, float sc, LAS float* scr, int lane) {
;     const int kr = lane >> 3, c4 = lane & 7;
;     f32x4 v[8];
; #pragma unroll
;     for (int i = 0; i < 8; ++i) v[i] = *(const f32x4*)(src + (size_t)(8 * i + kr) * ldw + 4 * c4);
; #pragma unroll
;     for (int i = 0; i < 8; ++i) { LAS float* d = scr + (8 * i + kr) * 33 + 4 * c4; d[0] = v[i].x; d[1] = v[i].y; d[2] = v[i].z; d[3] = v[i].w; }
;     asm volatile("s_waitcnt lgkmcnt(0)" ::: "memory");
;     const int c = lane & 7;
; #pragma unroll
;     for (int j = 0; j < 4; ++j) { const int n = (lane >> 3) + 8 * j; const LAS float* s = scr + (8 * c) * 33 + n;
;         int w0 = 0, w1 = 0; w0 = __builtin_amdgcn_cvt_pk_fp8_f32(s[0 * 33] * sc, s[1 * 33] * sc, w0, false); w0 = __builtin_amdgcn_cvt_pk_fp8_f32(s[2 * 33] * sc, s[3 * 33] * sc, w0, true);
;         w1 = __builtin_amdgcn_cvt_pk_fp8_f32(s[4 * 33] * sc, s[5 * 33] * sc, w1, false); w1 = __builtin_amdgcn_cvt_pk_fp8_f32(s[6 * 33] * sc, s[7 * 33] * sc, w1, true);
;         *(v2u*)(dst + (size_t)n * Kb + 8 * c) = (v2u){(unsigned)w0, (unsigned)w1}; }
;     asm volatile("s_waitcnt lgkmcnt(0)" ::: "memory");
; }
; template <int MAP> __device__ __forceinline__ void tr_seg8(const float* W, int ldw, int K, int c0, int ncols, unsigned char* WT, int row_off, int F, float sc, LAS float* scr, int item, int lane) {
;     const int nblk = ncols / 32, kb = item / nblk, nb = item % nblk, k0 = 64 * kb, n0 = 32 * nb;
;     int drow;
;     if (MAP == 0) drow = row_off + n0; else { int c = n0; const int up = c >= F; if (up) c -= F; drow = row_off + 256 * (c / 128) + 128 * up + (c % 128); }
;     tr_block8(W + (size_t)k0 * ldw + c0 + n0, ldw, WT + (size_t)drow * K + k0, K, sc, scr, lane);
; }
; template <int SEL> __global__ void __launch_bounds__(NWAVES * 64, 2) fwd_kernel(Args args) {
;     ...
;             if (r < I_DN) { if constexpr (DENSE_FP8 == 2) tr_seg8<0>(in[17], 1024, DFF, 0, 1024, (unsigned char*)q_Wdn_t, 0, 0, W8_SCALE, scr, r, lane); else tr_seg<0>(in[17], 1024, DFF, 0, 1024, q_Wdn_t, 0, 0, scr, r, lane); continue; } r -= I_DN;
.LBB0_18:
	s_andn2_b64 vcc, exec, s[18:19]
	s_cbranch_vccnz .LBB0_20
	s_mov_b64 s[18:19], s[0:1]
	s_load_dwordx2 s[20:21], s[18:19], 0x88
	s_add_i32 s52, s23, 0x1b200
	s_and_b32 s52, s52, 0x1ffc0
	s_and_b32 s53, s27, 0x3e0
	s_lshl_b32 s54, s52, 12
	s_waitcnt lgkmcnt(0)
	s_add_u32 s20, s20, s54
	s_addc_u32 s21, s21, 0
	s_lshl_b32 s54, s53, 2
	s_add_u32 s20, s20, s54
	s_addc_u32 s21, s21, 0
	v_lshl_add_u64 v[92:93], s[20:21], 0, v[2:3]
	v_mov_b32_e32 v59, v3
	v_mov_b32_e32 v61, v3
	v_mov_b32_e32 v63, v3
	v_lshlrev_b32_e32 v74, 2, v10
	v_mov_b32_e32 v75, v3
	v_lshlrev_b32_e32 v80, 2, v12
	v_mov_b32_e32 v81, v3
	v_lshlrev_b32_e32 v82, 2, v14
	v_mov_b32_e32 v83, v3
	s_mov_b64 s[18:19], s[0:1]
	v_lshl_add_u64 v[64:65], v[92:93], 0, v[58:59]
	v_lshl_add_u64 v[68:69], v[92:93], 0, v[60:61]
	v_lshl_add_u64 v[72:73], v[92:93], 0, v[62:63]
	v_lshl_add_u64 v[76:77], v[92:93], 0, v[74:75]
	v_lshl_add_u64 v[80:81], v[92:93], 0, v[80:81]
	v_lshl_add_u64 v[84:85], v[92:93], 0, v[82:83]
	global_load_dwordx4 v[64:67], v[64:65], off nt
	s_nop 0
	global_load_dwordx4 v[68:71], v[68:69], off nt
	s_nop 0
	global_load_dwordx4 v[72:75], v[72:73], off nt
	s_nop 0
	global_load_dwordx4 v[76:79], v[76:77], off nt
	s_nop 0
	global_load_dwordx4 v[80:83], v[80:81], off nt
	s_nop 0
	global_load_dwordx4 v[84:87], v[84:85], off nt
	v_lshlrev_b32_e32 v88, 2, v16
	v_mov_b32_e32 v89, v3
	v_lshl_add_u64 v[88:89], v[92:93], 0, v[88:89]
	global_load_dwordx4 v[88:91], v[88:89], off nt
	v_lshlrev_b32_e32 v94, 2, v18
	v_mov_b32_e32 v95, v3
	v_lshl_add_u64 v[92:93], v[92:93], 0, v[94:95]
	global_load_dwordx4 v[92:95], v[92:93], off nt
	v_add_u32_e32 v19, v13, v15
	v_add_u32_e32 v27, 0x420, v19
	v_add_u32_e32 v29, 0x428, v19
	v_add_u32_e32 v31, 0x840, v19
	v_add_u32_e32 v33, 0x848, v19
	v_add_u32_e32 v35, 0xc60, v19
	v_add_u32_e32 v37, 0xc68, v19
	v_add_u32_e32 v39, 0x1080, v19
	v_add_u32_e32 v41, 0x1088, v19
	v_add_u32_e32 v43, 0x14a0, v19
	v_add_u32_e32 v45, 0x14a8, v19
	s_load_dwordx2 s[18:19], s[18:19], 0xc0
	v_add_u32_e32 v47, 0x18c0, v19
	v_add_u32_e32 v49, 0x18c8, v19
	v_add_u32_e32 v51, 0x1ce0, v19
	v_add_u32_e32 v53, 0x1ce8, v19
	v_mov_b32_e32 v97, v3
	v_mov_b32_e32 v96, v3
	s_mulk_i32 s53, 0xb00
	s_waitcnt lgkmcnt(0)
	s_add_u32 s18, s18, s53
	s_addc_u32 s19, s19, 0
	s_add_u32 s18, s18, s52
	s_addc_u32 s19, s19, 0
	v_lshl_add_u64 v[98:99], s[18:19], 0, v[20:21]
	v_lshl_add_u64 v[98:99], v[98:99], 0, v[24:25]
	s_waitcnt vmcnt(7)
	ds_write2_b32 v19, v64, v65 offset1:1
	ds_write2_b32 v19, v66, v67 offset0:2 offset1:3
	s_waitcnt vmcnt(6)
	ds_write2_b32 v27, v68, v69 offset1:1
	ds_write2_b32 v29, v70, v71 offset1:1
	s_waitcnt vmcnt(5)
	ds_write2_b32 v31, v72, v73 offset1:1
	ds_write2_b32 v33, v74, v75 offset1:1
	s_waitcnt vmcnt(4)
	ds_write2_b32 v35, v76, v77 offset1:1
	ds_write2_b32 v37, v78, v79 offset1:1
	s_waitcnt vmcnt(3)
	ds_write2_b32 v39, v80, v81 offset1:1
	ds_write2_b32 v41, v82, v83 offset1:1
	s_waitcnt vmcnt(2)
	ds_write2_b32 v43, v84, v85 offset1:1
	ds_write2_b32 v45, v86, v87 offset1:1
	s_waitcnt vmcnt(1)
	ds_write2_b32 v47, v88, v89 offset1:1
	ds_write2_b32 v49, v90, v91 offset1:1
	s_waitcnt vmcnt(0)
	ds_write2_b32 v51, v92, v93 offset1:1
	ds_write2_b32 v53, v94, v95 offset1:1
	s_waitcnt lgkmcnt(0)
	ds_read2_b32 v[64:65], v17 offset1:8
	ds_read2_b32 v[66:67], v17 offset0:33 offset1:41
	ds_read2_b32 v[68:69], v17 offset0:66 offset1:74
	ds_read2_b32 v[70:71], v17 offset0:99 offset1:107
	ds_read2_b32 v[72:73], v17 offset0:132 offset1:140
	ds_read2_b32 v[74:75], v17 offset0:165 offset1:173
	ds_read2_b32 v[76:77], v17 offset0:198 offset1:206
	ds_read2_b32 v[78:79], v17 offset0:231 offset1:239
	s_waitcnt lgkmcnt(7)
	v_mul_f32_e32 v19, 0x42800000, v64
	s_waitcnt lgkmcnt(3)
	v_mul_f32_e32 v33, 0x42800000, v72
	s_waitcnt lgkmcnt(2)
	v_mul_f32_e32 v35, 0x42800000, v74
	v_mul_f32_e32 v27, 0x42800000, v66
	v_cvt_pk_fp8_f32 v97, v33, v35
	v_cvt_pk_fp8_f32 v96, v19, v27
	s_waitcnt lgkmcnt(1)
	v_mul_f32_e32 v19, 0x42800000, v76
	s_waitcnt lgkmcnt(0)
	v_mul_f32_e32 v27, 0x42800000, v78
	v_mul_f32_e32 v29, 0x42800000, v68
	v_mul_f32_e32 v31, 0x42800000, v70
	v_cvt_pk_fp8_f32 v97, v19, v27 op_sel:[0,0,1]
	v_mul_f32_e32 v19, 0x42800000, v65
	v_mul_f32_e32 v27, 0x42800000, v67
	v_mov_b32_e32 v64, v3
	v_cvt_pk_fp8_f32 v96, v29, v31 op_sel:[0,0,1]
	v_cvt_pk_fp8_f32 v64, v19, v27
	v_mul_f32_e32 v29, 0x42800000, v73
	v_mul_f32_e32 v31, 0x42800000, v75
	v_mov_b32_e32 v65, v3
	v_cvt_pk_fp8_f32 v65, v29, v31
	v_mul_f32_e32 v19, 0x42800000, v69
	v_mul_f32_e32 v27, 0x42800000, v71
	v_cvt_pk_fp8_f32 v64, v19, v27 op_sel:[0,0,1]
	v_mul_f32_e32 v19, 0x42800000, v77
	v_mul_f32_e32 v27, 0x42800000, v79
	v_add_co_u32_e32 v80, vcc, s39, v98
	v_cvt_pk_fp8_f32 v65, v19, v27 op_sel:[0,0,1]
	s_nop 0
	v_addc_co_u32_e32 v81, vcc, 0, v99, vcc
	v_add_co_u32_e32 v70, vcc, s40, v98
	global_store_dwordx2 v[80:81], v[96:97], off nt
	s_nop 0
	v_addc_co_u32_e32 v71, vcc, 0, v99, vcc
	ds_read2_b32 v[66:67], v17 offset0:16 offset1:24
	ds_read2_b32 v[68:69], v17 offset0:49 offset1:57
	global_store_dwordx2 v[70:71], v[64:65], off offset:2048 nt
	ds_read2_b32 v[70:71], v17 offset0:82 offset1:90
	ds_read2_b32 v[72:73], v17 offset0:115 offset1:123
	ds_read2_b32 v[74:75], v17 offset0:148 offset1:156
	ds_read2_b32 v[76:77], v17 offset0:181 offset1:189
	v_mov_b32_e32 v64, v3
	s_waitcnt lgkmcnt(5)
	v_mul_f32_e32 v19, 0x42800000, v66
	s_waitcnt lgkmcnt(4)
	v_mul_f32_e32 v27, 0x42800000, v68
	ds_read2_b32 v[78:79], v17 offset0:214 offset1:222
	ds_read2_b32 v[80:81], v17 offset0:247 offset1:255
	v_cvt_pk_fp8_f32 v64, v19, v27
	s_waitcnt lgkmcnt(3)
	v_mul_f32_e32 v29, 0x42800000, v74
	s_waitcnt lgkmcnt(2)
	v_mul_f32_e32 v31, 0x42800000, v76
	v_mov_b32_e32 v65, v3
	v_cvt_pk_fp8_f32 v65, v29, v31
	v_mul_f32_e32 v19, 0x42800000, v70
	v_mul_f32_e32 v27, 0x42800000, v72
	v_cvt_pk_fp8_f32 v64, v19, v27 op_sel:[0,0,1]
	s_waitcnt lgkmcnt(1)
	v_mul_f32_e32 v19, 0x42800000, v78
	s_waitcnt lgkmcnt(0)
	v_mul_f32_e32 v27, 0x42800000, v80
	v_cvt_pk_fp8_f32 v65, v19, v27 op_sel:[0,0,1]
	v_add_co_u32_e32 v82, vcc, s41, v98
	v_mul_f32_e32 v19, 0x42800000, v67
	s_nop 0
	v_addc_co_u32_e32 v83, vcc, 0, v99, vcc
	global_store_dwordx2 v[82:83], v[64:65], off nt
	v_mul_f32_e32 v27, 0x42800000, v69
	v_mov_b32_e32 v64, v3
	v_cvt_pk_fp8_f32 v64, v19, v27
	v_mul_f32_e32 v29, 0x42800000, v75
	v_mul_f32_e32 v31, 0x42800000, v77
	v_mov_b32_e32 v65, v3
	v_cvt_pk_fp8_f32 v65, v29, v31
	v_mul_f32_e32 v19, 0x42800000, v71
	v_mul_f32_e32 v27, 0x42800000, v73
	v_cvt_pk_fp8_f32 v64, v19, v27 op_sel:[0,0,1]
	v_mul_f32_e32 v19, 0x42800000, v79
	v_mul_f32_e32 v27, 0x42800000, v81
	v_cvt_pk_fp8_f32 v65, v19, v27 op_sel:[0,0,1]
	v_add_co_u32_e32 v66, vcc, 0x3710000, v98
	s_nop 1
	v_addc_co_u32_e32 v67, vcc, 0, v99, vcc
	global_store_dwordx2 v[66:67], v[64:65], off offset:2048 nt
	s_waitcnt lgkmcnt(0)

; #define LAS __attribute__((address_space(3)))
; #define in KArgIn()
; __device__ __forceinline__ void tr_block8(const float* src, int ldw, unsigned char* dst  , int Kb, float sc, LAS float* scr, int lane) {
;     const int kr = lane >> 3, c4 = lane & 7;
;     f32x4 v[8];
; #pragma unroll
;     for (int i = 0; i < 8; ++i) v[i] = *(const f32x4*)(src + (size_t)(8 * i + kr) * ldw + 4 * c4);
; #pragma unroll
;     for (int i = 0; i < 8; ++i) { LAS float* d = scr + (8 * i + kr) * 33 + 4 * c4; d[0] = v[i].x; d[1] = v[i].y; d[2] = v[i].z; d[3] = v[i].w; }
;     asm volatile("s_waitcnt lgkmcnt(0)" ::: "memory");
;     const int c = lane & 7;
; #pragma unroll
;     for (int j = 0; j < 4; ++j) { const int n = (lane >> 3) + 8 * j; const LAS float* s = scr + (8 * c) * 33 + n;
;         int w0 = 0, w1 = 0; w0 = __builtin_amdgcn_cvt_pk_fp8_f32(s[0 * 33] * sc, s[1 * 33] * sc, w0, false); w0 = __builtin_amdgcn_cvt_pk_fp8_f32(s[2 * 33] * sc, s[3 * 33] * sc, w0, true);
;         w1 = __builtin_amdgcn_cvt_pk_fp8_f32(s[4 * 33] * sc, s[5 * 33] * sc, w1, false); w1 = __builtin_amdgcn_cvt_pk_fp8_f32(s[6 * 33] * sc, s[7 * 33] * sc, w1, true);
;         *(v2u*)(dst + (size_t)n * Kb + 8 * c) = (v2u){(unsigned)w0, (unsigned)w1}; }
;     asm volatile("s_waitcnt lgkmcnt(0)" ::: "memory");
; }
; template <int MAP> __device__ __forceinline__ void tr_seg8(const float* W, int ldw, int K, int c0, int ncols, unsigned char* WT, int row_off, int F, float sc, LAS float* scr, int item, int lane) {
;     const int nblk = ncols / 32, kb = item / nblk, nb = item % nblk, k0 = 64 * kb, n0 = 32 * nb;
;     int drow;
;     if (MAP == 0) drow = row_off + n0; else { int c = n0; const int up = c >= F; if (up) c -= F; drow = row_off + 256 * (c / 128) + 128 * up + (c % 128); }
;     tr_block8(W + (size_t)k0 * ldw + c0 + n0, ldw, WT + (size_t)drow * K + k0, K, sc, scr, lane);
; }
; template <int SEL> __global__ void __launch_bounds__(NWAVES * 64, 2) fwd_kernel(Args args) {
;     ...
;             if (r < I_GU) { if constexpr (DENSE_FP8 != 0) tr_seg8<1>(in[16], 2 * DFF, 1024, 0, 2 * DFF, (unsigned char*)q_Wgu_t, 0, DFF, W8_SCALE, scr, r, lane); else tr_seg<1>(in[16], 2 * DFF, 1024, 0, 2 * DFF, q_Wgu_t, 0, DFF, scr, r, lane); continue; } r -= I_GU;
.LBB0_21:
	s_andn2_b64 vcc, exec, s[18:19]
	s_cbranch_vccnz .LBB0_23
	s_add_i32 s20, s4, 0xe400
	s_and_b32 s21, s20, 0xffff
	s_mul_i32 s21, s21, 0xba2f
	s_lshr_b32 s21, s21, 23
	s_mul_i32 s54, s21, 0xb0
	s_sub_i32 s54, s20, s54
	s_lshl_b32 s20, s54, 5
	s_and_b32 s55, s54, 0xffff
	s_cmpk_lt_u32 s55, 0x58
	s_cselect_b32 s56, 0, 0xfffff500
	s_cselect_b32 s55, 0, 0x80
	s_add_i32 s20, s56, s20
	s_sext_i32_i16 s57, s20
	s_bfe_u32 s57, s57, 0x70018
	s_mov_b64 s[18:19], s[0:1]
	s_add_i32 s57, s20, s57
	s_load_dwordx2 s[52:53], s[18:19], 0x80
	s_sext_i32_i16 s58, s57
	s_and_b32 s57, s57, 0xff80
	s_sub_i32 s20, s20, s57
	s_lshl_b32 s58, s58, 1
	s_sext_i32_i16 s20, s20
	s_and_b32 s58, s58, 0xffffff00
	s_add_i32 s20, s55, s20
	s_lshl_b32 s56, s21, 6
	s_add_i32 s20, s20, s58
	s_mul_i32 s21, s21, 0x160000
	s_waitcnt lgkmcnt(0)
	s_add_u32 s21, s52, s21
	s_addc_u32 s53, s53, 0
	s_lshl_b32 s52, s54, 7
	s_and_b32 s52, s52, 0x3ff80
	s_add_u32 s52, s21, s52
	s_addc_u32 s53, s53, 0
	v_lshl_add_u64 v[92:93], s[52:53], 0, v[2:3]
	v_mov_b32_e32 v51, v3
	v_lshl_add_u64 v[88:89], v[92:93], 0, v[50:51]
	v_add_co_u32_e32 v68, vcc, s42, v88
	v_mov_b32_e32 v55, v3
	s_nop 0
	v_addc_co_u32_e32 v69, vcc, 0, v89, vcc
	v_add_co_u32_e32 v80, vcc, s43, v88
	v_mov_b32_e32 v57, v3
	s_nop 0
	v_addc_co_u32_e32 v81, vcc, 0, v89, vcc
	v_add_co_u32_e32 v84, vcc, s44, v88
	s_mov_b64 s[18:19], s[0:1]
	s_nop 0
	v_addc_co_u32_e32 v85, vcc, 0, v89, vcc
	v_lshl_add_u64 v[72:73], v[92:93], 0, v[54:55]
	v_lshl_add_u64 v[76:77], v[92:93], 0, v[56:57]
	global_load_dwordx4 v[64:67], v[88:89], off nt
	s_nop 0
	global_load_dwordx4 v[68:71], v[68:69], off nt
	v_add_co_u32_e32 v88, vcc, s45, v88
	global_load_dwordx4 v[72:75], v[72:73], off nt
	s_nop 0
	global_load_dwordx4 v[76:79], v[76:77], off nt
	s_nop 0
	global_load_dwordx4 v[80:83], v[80:81], off nt
	s_nop 0
	global_load_dwordx4 v[84:87], v[84:85], off nt
	v_addc_co_u32_e32 v89, vcc, 0, v89, vcc
	global_load_dwordx4 v[88:91], v[88:89], off nt
	v_mov_b32_e32 v53, v3
	v_lshl_add_u64 v[92:93], v[92:93], 0, v[52:53]
	global_load_dwordx4 v[92:95], v[92:93], off nt
	v_add_u32_e32 v19, v13, v15
	v_add_u32_e32 v27, 0x420, v19
	v_add_u32_e32 v29, 0x428, v19
	v_add_u32_e32 v31, 0x840, v19
	v_add_u32_e32 v33, 0x848, v19
	v_add_u32_e32 v35, 0xc60, v19
	v_add_u32_e32 v37, 0xc68, v19
	v_add_u32_e32 v39, 0x1080, v19
	v_add_u32_e32 v41, 0x1088, v19
	v_add_u32_e32 v43, 0x14a0, v19
	v_add_u32_e32 v45, 0x14a8, v19
	v_add_u32_e32 v47, 0x18c0, v19
	v_add_u32_e32 v49, 0x18c8, v19
	s_load_dwordx2 s[18:19], s[18:19], 0xc0
	v_add_u32_e32 v51, 0x1ce0, v19
	v_add_u32_e32 v53, 0x1ce8, v19
	s_ashr_i32 s21, s20, 31
	s_lshl_b64 s[20:21], s[20:21], 10
	s_waitcnt lgkmcnt(0)
	s_add_u32 s18, s18, s20
	s_addc_u32 s19, s19, s21
	s_add_u32 s18, s18, s56
	s_addc_u32 s19, s19, 0
	s_waitcnt vmcnt(7)
	ds_write2_b32 v19, v64, v65 offset1:1
	ds_write2_b32 v19, v66, v67 offset0:2 offset1:3
	s_waitcnt vmcnt(5)
	ds_write2_b32 v47, v72, v73 offset1:1
	ds_write2_b32 v49, v74, v75 offset1:1
	s_waitcnt vmcnt(4)
	ds_write2_b32 v51, v76, v77 offset1:1
	ds_write2_b32 v53, v78, v79 offset1:1
	ds_write2_b32 v27, v68, v69 offset1:1
	ds_write2_b32 v29, v70, v71 offset1:1
	s_waitcnt vmcnt(3)
	ds_write2_b32 v31, v80, v81 offset1:1
	ds_write2_b32 v33, v82, v83 offset1:1
	s_waitcnt vmcnt(2)
	ds_write2_b32 v35, v84, v85 offset1:1
	ds_write2_b32 v37, v86, v87 offset1:1
	s_waitcnt vmcnt(1)
	ds_write2_b32 v39, v88, v89 offset1:1
	ds_write2_b32 v41, v90, v91 offset1:1
	s_waitcnt vmcnt(0)
	ds_write2_b32 v43, v92, v93 offset1:1
	ds_write2_b32 v45, v94, v95 offset1:1
	s_waitcnt lgkmcnt(0)
; #define LAS __attribute__((address_space(3)))
; __device__ __forceinline__ void tr_block8(const float* src, int ldw, unsigned char* dst  , int Kb, float sc, LAS float* scr, int lane) {
;     ...
;     const int c = lane & 7;
; #pragma unroll
;     for (int j = 0; j < 4; ++j) { const int n = (lane >> 3) + 8 * j; const LAS float* s = scr + (8 * c) * 33 + n;
;         int w0 = 0, w1 = 0; w0 = __builtin_amdgcn_cvt_pk_fp8_f32(s[0 * 33] * sc, s[1 * 33] * sc, w0, false); w0 = __builtin_amdgcn_cvt_pk_fp8_f32(s[2 * 33] * sc, s[3 * 33] * sc, w0, true);
;         w1 = __builtin_amdgcn_cvt_pk_fp8_f32(s[4 * 33] * sc, s[5 * 33] * sc, w1, false); w1 = __builtin_amdgcn_cvt_pk_fp8_f32(s[6 * 33] * sc, s[7 * 33] * sc, w1, true);
;         *(v2u*)(dst + (size_t)n * Kb + 8 * c) = (v2u){(unsigned)w0, (unsigned)w1}; }
;     asm volatile("s_waitcnt lgkmcnt(0)" ::: "memory");
	ds_read2_b32 v[64:65], v17 offset1:8
	ds_read2_b32 v[66:67], v17 offset0:33 offset1:41
	ds_read2_b32 v[72:73], v17 offset0:66 offset1:74
	ds_read2_b32 v[74:75], v17 offset0:99 offset1:107
	ds_read2_b32 v[76:77], v17 offset0:132 offset1:140
	ds_read2_b32 v[78:79], v17 offset0:165 offset1:173
	v_mov_b32_e32 v70, v3
	ds_read2_b32 v[80:81], v17 offset0:198 offset1:206
	ds_read2_b32 v[82:83], v17 offset0:231 offset1:239
	s_waitcnt lgkmcnt(7)
	v_mul_f32_e32 v19, 0x42800000, v64
	s_waitcnt lgkmcnt(6)
	v_mul_f32_e32 v27, 0x42800000, v66
	v_cvt_pk_fp8_f32 v70, v19, v27
	s_waitcnt lgkmcnt(3)
	v_mul_f32_e32 v29, 0x42800000, v76
	s_waitcnt lgkmcnt(2)
	v_mul_f32_e32 v31, 0x42800000, v78
	v_mov_b32_e32 v71, v3
	v_cvt_pk_fp8_f32 v71, v29, v31
	v_mul_f32_e32 v19, 0x42800000, v72
	v_mul_f32_e32 v27, 0x42800000, v74
	v_cvt_pk_fp8_f32 v70, v19, v27 op_sel:[0,0,1]
	s_waitcnt lgkmcnt(1)
	v_mul_f32_e32 v19, 0x42800000, v80
	s_waitcnt lgkmcnt(0)
	v_mul_f32_e32 v27, 0x42800000, v82
	v_cvt_pk_fp8_f32 v71, v19, v27 op_sel:[0,0,1]
	v_mul_f32_e32 v19, 0x42800000, v65
	v_mul_f32_e32 v27, 0x42800000, v67
	v_mov_b32_e32 v64, v3
	v_cvt_pk_fp8_f32 v64, v19, v27
	v_mul_f32_e32 v29, 0x42800000, v77
	v_mul_f32_e32 v31, 0x42800000, v79
	v_mov_b32_e32 v65, v3
	v_cvt_pk_fp8_f32 v65, v29, v31
	v_mul_f32_e32 v19, 0x42800000, v73
	v_mul_f32_e32 v27, 0x42800000, v75
	v_cvt_pk_fp8_f32 v64, v19, v27 op_sel:[0,0,1]
	v_mul_f32_e32 v19, 0x42800000, v81
	v_mul_f32_e32 v27, 0x42800000, v83
	v_lshl_add_u64 v[68:69], s[18:19], 0, v[20:21]
	v_cvt_pk_fp8_f32 v65, v19, v27 op_sel:[0,0,1]
	v_lshl_add_u64 v[68:69], v[68:69], 0, s[8:9]
	v_lshl_add_u64 v[84:85], v[68:69], 0, v[4:5]
	ds_read2_b32 v[66:67], v17 offset0:16 offset1:24
	ds_read2_b32 v[72:73], v17 offset0:49 offset1:57
	global_store_dwordx2 v[84:85], v[70:71], off nt
	v_lshl_add_u64 v[70:71], v[68:69], 0, v[6:7]
	global_store_dwordx2 v[70:71], v[64:65], off nt
	ds_read2_b32 v[70:71], v17 offset0:82 offset1:90
	ds_read2_b32 v[74:75], v17 offset0:115 offset1:123
	ds_read2_b32 v[76:77], v17 offset0:148 offset1:156
	ds_read2_b32 v[78:79], v17 offset0:181 offset1:189
	s_waitcnt lgkmcnt(5)
	v_mul_f32_e32 v19, 0x42800000, v66
	s_waitcnt lgkmcnt(4)
	v_mul_f32_e32 v27, 0x42800000, v72
	v_mov_b32_e32 v64, v3
	ds_read2_b32 v[80:81], v17 offset0:214 offset1:222
	ds_read2_b32 v[82:83], v17 offset0:247 offset1:255
	v_cvt_pk_fp8_f32 v64, v19, v27
	s_waitcnt lgkmcnt(3)
	v_mul_f32_e32 v29, 0x42800000, v76
	s_waitcnt lgkmcnt(2)
	v_mul_f32_e32 v31, 0x42800000, v78
	v_mov_b32_e32 v65, v3
	v_cvt_pk_fp8_f32 v65, v29, v31
	v_mul_f32_e32 v19, 0x42800000, v70
	v_mul_f32_e32 v27, 0x42800000, v74
	v_cvt_pk_fp8_f32 v64, v19, v27 op_sel:[0,0,1]
	s_waitcnt lgkmcnt(1)
	v_mul_f32_e32 v19, 0x42800000, v80
	s_waitcnt lgkmcnt(0)
	v_mul_f32_e32 v27, 0x42800000, v82
	v_cvt_pk_fp8_f32 v65, v19, v27 op_sel:[0,0,1]
	v_mul_f32_e32 v19, 0x42800000, v67
	v_mul_f32_e32 v27, 0x42800000, v73
	v_mov_b32_e32 v66, v3
	v_cvt_pk_fp8_f32 v66, v19, v27
	v_mul_f32_e32 v29, 0x42800000, v77
	v_mul_f32_e32 v31, 0x42800000, v79
	v_mov_b32_e32 v67, v3
	v_cvt_pk_fp8_f32 v67, v29, v31
	v_mul_f32_e32 v19, 0x42800000, v71
	v_mul_f32_e32 v27, 0x42800000, v75
	v_cvt_pk_fp8_f32 v66, v19, v27 op_sel:[0,0,1]
	v_mul_f32_e32 v19, 0x42800000, v81
	v_mul_f32_e32 v27, 0x42800000, v83
	v_cvt_pk_fp8_f32 v67, v19, v27 op_sel:[0,0,1]
	v_lshl_add_u64 v[70:71], v[68:69], 0, v[8:9]
	global_store_dwordx2 v[70:71], v[64:65], off nt
	v_lshl_add_u64 v[64:65], v[68:69], 0, v[10:11]
	global_store_dwordx2 v[64:65], v[66:67], off nt
	s_waitcnt lgkmcnt(0)

; #define LAS __attribute__((address_space(3)))
; __device__ __forceinline__ unsigned pk2(float lo, float hi) { return f2bf(lo) | (f2bf(hi) << 16); }
; #define in KArgIn()
; __device__ __forceinline__ void tr_block(const float* src  , int ldw, bf16* dst  , int K, LAS float* scr, int lane) {
;     const int kr = lane >> 3, c4 = lane & 7;
;     f32x4 v[8];
; #pragma unroll
;     for (int i = 0; i < 8; ++i) v[i] = *(const f32x4*)(src + (size_t)(8 * i + kr) * ldw + 4 * c4);
; #pragma unroll
;     for (int i = 0; i < 8; ++i) { LAS float* d = scr + (8 * i + kr) * 33 + 4 * c4; d[0] = v[i].x; d[1] = v[i].y; d[2] = v[i].z; d[3] = v[i].w; }
;     asm volatile("s_waitcnt lgkmcnt(0)" ::: "memory");
;     const int c = lane & 7;
; #pragma unroll
;     for (int j = 0; j < 4; ++j) { const int n = (lane >> 3) + 8 * j; const LAS float* s = scr + (8 * c) * 33 + n;
;         v4u o; o.x = pk2(s[0 * 33], s[1 * 33]); o.y = pk2(s[2 * 33], s[3 * 33]); o.z = pk2(s[4 * 33], s[5 * 33]); o.w = pk2(s[6 * 33], s[7 * 33]);
;         *(v4u*)(dst + (size_t)n * K + 8 * c) = o; }
;     asm volatile("s_waitcnt lgkmcnt(0)" ::: "memory");
; template <int SEL> __global__ void __launch_bounds__(NWAVES * 64, 2) fwd_kernel(Args args) {
;     ...
;             if (r < 2 * I_L) { const int l = r / I_L; r -= l * I_L; const float* win = in[3] + (size_t)l * 1024 * NIN; bf16* wt = q_Win_t + (size_t)l * NPROJ * 1024;
;                 if (r < I_A) { tr_seg<0>(win, NIN, 1024, 0, 1536, wt, 0, 0, scr, r, lane); continue; } r -= I_A;
;                 if (r < I_B) { tr_seg<0>(win, NIN, 1024, 1544, 3584, wt, 1536, 0, scr, r, lane); continue; } r -= I_B;
;                 if (r < I_BR) { tr_seg<0>(in[10] + (size_t)l * 512 * 1024, 1024, 512, 0, 1024, q_Wbr_t + (size_t)l * 2048 * 512, 0, 0, scr, r, lane); continue; } r -= I_BR;
;                 if (r < I_BR) { tr_seg<0>(in[11] + (size_t)l * 512 * 1024, 1024, 512, 0, 1024, q_Wbr_t + (size_t)l * 2048 * 512, 1024, 0, scr, r, lane); continue; } r -= I_BR;
;                 tr_seg<0>(in[12] + (size_t)l * 1024 * 1024, 1024, 1024, 0, 1024, q_Wo_t + (size_t)l * 1024 * 1024, 0, 0, scr, r, lane); continue; }
.LBB0_24:
	s_andn2_b64 vcc, exec, s[18:19]
	s_cbranch_vccnz .LBB0_9
	s_mul_hi_i32 s18, s4, 0x92492493
	s_mov_b64 s[20:21], s[0:1]
	s_add_i32 s18, s18, s4
	s_lshr_b32 s4, s18, 31
	s_ashr_i32 s18, s18, 11
	s_load_dwordx2 s[20:21], s[20:21], 0x18
	s_mov_b64 s[52:53], s[0:1]
	s_add_i32 s18, s18, s4
	s_mul_i32 s4, s18, 0xfffff200
	s_load_dwordx2 s[52:53], s[52:53], 0xc0
	s_add_i32 s54, s3, s4
	s_add_i32 s54, s54, 0x9c80
	s_mul_i32 s19, s18, 0x1408000
	s_mul_hi_i32 s4, s18, 0x1408000
	s_waitcnt lgkmcnt(0)
	s_add_u32 s55, s20, s19
	s_addc_u32 s56, s21, s4
	s_mul_i32 s19, s18, 0xa00000
	s_mul_hi_i32 s4, s18, 0xa00000
	s_add_u32 s19, s52, s19
	s_addc_u32 s4, s53, s4
	s_add_u32 s52, s19, 0x1000000
	s_addc_u32 s53, s4, 0
	s_cmpk_gt_i32 s54, 0x2ff
	s_mov_b64 s[20:21], -1
	s_cbranch_scc0 .LBB0_39
	s_cmpk_gt_u32 s54, 0x9ff
	s_cbranch_scc0 .LBB0_36
	s_ashr_i32 s19, s18, 31
	s_cmpk_gt_u32 s54, 0xaff
	s_cbranch_scc0 .LBB0_33
	s_cmpk_gt_u32 s54, 0xbff
	s_cbranch_scc0 .LBB0_30
	s_mov_b64 s[20:21], s[0:1]
	s_load_dwordx2 s[20:21], s[20:21], 0x60
	s_mov_b64 s[58:59], s[0:1]
	s_load_dwordx2 s[58:59], s[58:59], 0xc0
	s_lshl_b64 s[60:61], s[18:19], 22
	s_waitcnt lgkmcnt(0)
	s_add_u32 s57, s20, s60
	s_addc_u32 s60, s21, s61
	s_lshl_b64 s[20:21], s[18:19], 21
	s_add_u32 s58, s58, s20
	s_mul_i32 s4, s18, 0xffffe400
	s_addc_u32 s59, s59, s21
	s_add_i32 s4, s23, s4
	s_andn2_b32 s4, s4, 63
	s_addk_i32 s4, 0xe800
	s_and_b32 s61, s27, 0x3e0
	s_lshl_b64 s[20:21], s[4:5], 12
	s_add_u32 s20, s57, s20
	s_addc_u32 s21, s60, s21
	s_lshl_b32 s57, s61, 2
	s_add_u32 s20, s20, s57
	s_addc_u32 s21, s21, 0
	v_lshl_add_u64 v[92:93], s[20:21], 0, v[2:3]
	v_mov_b32_e32 v59, v3
	v_mov_b32_e32 v61, v3
	v_mov_b32_e32 v63, v3
	v_lshlrev_b32_e32 v74, 2, v10
	v_mov_b32_e32 v75, v3
	v_lshlrev_b32_e32 v80, 2, v12
	v_mov_b32_e32 v81, v3
	v_lshlrev_b32_e32 v82, 2, v14
	v_mov_b32_e32 v83, v3
	v_lshl_add_u64 v[64:65], v[92:93], 0, v[58:59]
	v_lshl_add_u64 v[68:69], v[92:93], 0, v[60:61]
	v_lshl_add_u64 v[72:73], v[92:93], 0, v[62:63]
	v_lshl_add_u64 v[76:77], v[92:93], 0, v[74:75]
	v_lshl_add_u64 v[80:81], v[92:93], 0, v[80:81]
	v_lshl_add_u64 v[84:85], v[92:93], 0, v[82:83]
	global_load_dwordx4 v[64:67], v[64:65], off nt
	s_nop 0
	global_load_dwordx4 v[68:71], v[68:69], off nt
	s_nop 0
	global_load_dwordx4 v[72:75], v[72:73], off nt
	s_nop 0
	global_load_dwordx4 v[76:79], v[76:77], off nt
	s_nop 0
	global_load_dwordx4 v[80:83], v[80:81], off nt
	s_nop 0
	global_load_dwordx4 v[84:87], v[84:85], off nt
	v_lshlrev_b32_e32 v88, 2, v16
	v_mov_b32_e32 v89, v3
	v_lshl_add_u64 v[88:89], v[92:93], 0, v[88:89]
	global_load_dwordx4 v[88:91], v[88:89], off nt
	v_lshlrev_b32_e32 v94, 2, v18
	v_mov_b32_e32 v95, v3
	v_lshl_add_u64 v[92:93], v[92:93], 0, v[94:95]
	global_load_dwordx4 v[92:95], v[92:93], off nt
	v_add_u32_e32 v19, v13, v15
	v_add_u32_e32 v27, 0x420, v19
	v_add_u32_e32 v29, 0x428, v19
	v_add_u32_e32 v31, 0x840, v19
	v_add_u32_e32 v33, 0x848, v19
	v_add_u32_e32 v35, 0xc60, v19
	v_add_u32_e32 v37, 0xc68, v19
	v_add_u32_e32 v39, 0x1080, v19
	v_add_u32_e32 v41, 0x1088, v19
	v_add_u32_e32 v43, 0x14a0, v19
	v_add_u32_e32 v45, 0x14a8, v19
	v_add_u32_e32 v47, 0x18c0, v19
	v_add_u32_e32 v49, 0x18c8, v19
	v_add_u32_e32 v51, 0x1ce0, v19
	v_add_u32_e32 v53, 0x1ce8, v19
	s_lshl_b32 s20, s61, 11
	s_add_u32 s57, s58, s20
	s_addc_u32 s58, s59, 0
	s_lshl_b64 s[20:21], s[4:5], 1
	s_add_u32 s20, s57, s20
	v_lshlrev_b32_e32 v96, 1, v20
	v_mov_b32_e32 v97, v3
	s_addc_u32 s21, s58, s21
	v_lshl_add_u64 v[96:97], s[20:21], 0, v[96:97]
	v_lshl_add_u64 v[96:97], v[96:97], 0, s[10:11]
	s_mov_b64 s[20:21], 0
	s_waitcnt vmcnt(7)
	ds_write2_b32 v19, v64, v65 offset1:1
	ds_write2_b32 v19, v66, v67 offset0:2 offset1:3
	s_waitcnt vmcnt(6)
	ds_write2_b32 v27, v68, v69 offset1:1
	ds_write2_b32 v29, v70, v71 offset1:1
	s_waitcnt vmcnt(5)
	ds_write2_b32 v31, v72, v73 offset1:1
	ds_write2_b32 v33, v74, v75 offset1:1
	s_waitcnt vmcnt(4)
	ds_write2_b32 v35, v76, v77 offset1:1
	ds_write2_b32 v37, v78, v79 offset1:1
	s_waitcnt vmcnt(3)
	ds_write2_b32 v39, v80, v81 offset1:1
	ds_write2_b32 v41, v82, v83 offset1:1
	s_waitcnt vmcnt(2)
	ds_write2_b32 v43, v84, v85 offset1:1
	ds_write2_b32 v45, v86, v87 offset1:1
	s_waitcnt vmcnt(1)
	ds_write2_b32 v47, v88, v89 offset1:1
	ds_write2_b32 v49, v90, v91 offset1:1
	s_waitcnt vmcnt(0)
	ds_write2_b32 v51, v92, v93 offset1:1
	ds_write2_b32 v53, v94, v95 offset1:1
	s_waitcnt lgkmcnt(0)
	ds_read2_b32 v[68:69], v17 offset1:8
	ds_read2_b32 v[70:71], v17 offset0:33 offset1:41
	ds_read2_b32 v[72:73], v17 offset0:66 offset1:74
	ds_read2_b32 v[74:75], v17 offset0:99 offset1:107
	ds_read2_b32 v[76:77], v17 offset0:132 offset1:140
	ds_read2_b32 v[78:79], v17 offset0:165 offset1:173
	s_waitcnt lgkmcnt(5)
	v_bfe_u32 v19, v68, 16, 1
	s_waitcnt lgkmcnt(4)
	v_bfe_u32 v27, v70, 16, 1
	v_add3_u32 v19, v68, v19, s46
	ds_read2_b32 v[80:81], v17 offset0:198 offset1:206
	v_add3_u32 v27, v70, v27, s46
	v_lshrrev_b32_e32 v19, 16, v19
	ds_read2_b32 v[82:83], v17 offset0:231 offset1:239
	v_and_or_b32 v64, v27, s47, v19
	s_waitcnt lgkmcnt(3)
	v_bfe_u32 v19, v76, 16, 1
	v_add3_u32 v19, v76, v19, s46
	s_waitcnt lgkmcnt(2)
	v_bfe_u32 v27, v78, 16, 1
	v_lshrrev_b32_e32 v19, 16, v19
	v_add3_u32 v27, v78, v27, s46
	v_and_or_b32 v66, v27, s47, v19
	s_waitcnt lgkmcnt(1)
	v_bfe_u32 v19, v80, 16, 1
	v_add3_u32 v19, v80, v19, s46
	s_waitcnt lgkmcnt(0)
; #define LAS __attribute__((address_space(3)))
; __device__ __forceinline__ unsigned pk2(float lo, float hi) { return f2bf(lo) | (f2bf(hi) << 16); }
; #define in KArgIn()
; __device__ __forceinline__ void tr_block(const float* src  , int ldw, bf16* dst  , int K, LAS float* scr, int lane) {
;     const int kr = lane >> 3, c4 = lane & 7;
;     f32x4 v[8];
; #pragma unroll
;     for (int i = 0; i < 8; ++i) v[i] = *(const f32x4*)(src + (size_t)(8 * i + kr) * ldw + 4 * c4);
; #pragma unroll
;     for (int i = 0; i < 8; ++i) { LAS float* d = scr + (8 * i + kr) * 33 + 4 * c4; d[0] = v[i].x; d[1] = v[i].y; d[2] = v[i].z; d[3] = v[i].w; }
;     asm volatile("s_waitcnt lgkmcnt(0)" ::: "memory");
;     const int c = lane & 7;
; #pragma unroll
;     for (int j = 0; j < 4; ++j) { const int n = (lane >> 3) + 8 * j; const LAS float* s = scr + (8 * c) * 33 + n;
;         v4u o; o.x = pk2(s[0 * 33], s[1 * 33]); o.y = pk2(s[2 * 33], s[3 * 33]); o.z = pk2(s[4 * 33], s[5 * 33]); o.w = pk2(s[6 * 33], s[7 * 33]);
;         *(v4u*)(dst + (size_t)n * K + 8 * c) = o; }
;     asm volatile("s_waitcnt lgkmcnt(0)" ::: "memory");
; template <int SEL> __global__ void __launch_bounds__(NWAVES * 64, 2) fwd_kernel(Args args) {
;     ...
;                 if (r < I_BR) { tr_seg<0>(in[11] + (size_t)l * 512 * 1024, 1024, 512, 0, 1024, q_Wbr_t + (size_t)l * 2048 * 512, 1024, 0, scr, r, lane); continue; } r -= I_BR;
	v_bfe_u32 v27, v82, 16, 1
	v_bfe_u32 v29, v72, 16, 1
	v_lshrrev_b32_e32 v19, 16, v19
	v_add3_u32 v27, v82, v27, s46
	v_bfe_u32 v31, v74, 16, 1
	v_add3_u32 v29, v72, v29, s46
	v_and_or_b32 v67, v27, s47, v19
	v_bfe_u32 v19, v69, 16, 1
	v_add3_u32 v31, v74, v31, s46
	v_lshrrev_b32_e32 v29, 16, v29
	v_lshlrev_b32_e32 v84, 1, v4
	v_mov_b32_e32 v85, v3
	v_add3_u32 v19, v69, v19, s46
	v_bfe_u32 v27, v71, 16, 1
	v_and_or_b32 v65, v31, s47, v29
	v_lshl_add_u64 v[84:85], v[96:97], 0, v[84:85]
	v_lshrrev_b32_e32 v19, 16, v19
	v_add3_u32 v27, v71, v27, s46
	global_store_dwordx4 v[84:85], v[64:67], off nt
	v_lshlrev_b32_e32 v68, 1, v6
	v_mov_b32_e32 v69, v3
	v_and_or_b32 v64, v27, s47, v19
	v_bfe_u32 v19, v73, 16, 1
	v_add3_u32 v19, v73, v19, s46
	v_bfe_u32 v27, v75, 16, 1
	v_lshrrev_b32_e32 v19, 16, v19
	v_add3_u32 v27, v75, v27, s46
	v_and_or_b32 v65, v27, s47, v19
	v_bfe_u32 v19, v77, 16, 1
	v_add3_u32 v19, v77, v19, s46
	v_bfe_u32 v27, v79, 16, 1
	v_lshrrev_b32_e32 v19, 16, v19
	v_add3_u32 v27, v79, v27, s46
	v_and_or_b32 v66, v27, s47, v19
	v_bfe_u32 v19, v81, 16, 1
	v_add3_u32 v19, v81, v19, s46
	v_bfe_u32 v27, v83, 16, 1
	v_lshrrev_b32_e32 v19, 16, v19
	v_add3_u32 v27, v83, v27, s46
	v_and_or_b32 v67, v27, s47, v19
	ds_read2_b32 v[70:71], v17 offset0:16 offset1:24
	v_lshl_add_u64 v[68:69], v[96:97], 0, v[68:69]
	global_store_dwordx4 v[68:69], v[64:67], off nt
	ds_read2_b32 v[68:69], v17 offset0:49 offset1:57
	ds_read2_b32 v[72:73], v17 offset0:82 offset1:90
	ds_read2_b32 v[74:75], v17 offset0:115 offset1:123
	s_waitcnt lgkmcnt(3)
	v_bfe_u32 v19, v70, 16, 1
	v_add3_u32 v19, v70, v19, s46
	s_waitcnt lgkmcnt(2)
	v_bfe_u32 v27, v68, 16, 1
	ds_read2_b32 v[76:77], v17 offset0:148 offset1:156
	v_lshrrev_b32_e32 v19, 16, v19
	v_add3_u32 v27, v68, v27, s46
	ds_read2_b32 v[78:79], v17 offset0:181 offset1:189
	v_and_or_b32 v64, v27, s47, v19
	s_waitcnt lgkmcnt(3)
	v_bfe_u32 v19, v72, 16, 1
	v_add3_u32 v19, v72, v19, s46
	s_waitcnt lgkmcnt(2)
	v_bfe_u32 v27, v74, 16, 1
	ds_read2_b32 v[80:81], v17 offset0:214 offset1:222
	v_lshrrev_b32_e32 v19, 16, v19
	v_add3_u32 v27, v74, v27, s46
	ds_read2_b32 v[82:83], v17 offset0:247 offset1:255
	v_and_or_b32 v65, v27, s47, v19
	s_waitcnt lgkmcnt(3)
	v_bfe_u32 v19, v76, 16, 1
	v_add3_u32 v19, v76, v19, s46
	s_waitcnt lgkmcnt(2)
	v_bfe_u32 v27, v78, 16, 1
	v_lshrrev_b32_e32 v19, 16, v19
	v_add3_u32 v27, v78, v27, s46
	v_and_or_b32 v66, v27, s47, v19
	s_waitcnt lgkmcnt(1)
	v_bfe_u32 v19, v80, 16, 1
	v_add3_u32 v19, v80, v19, s46
	s_waitcnt lgkmcnt(0)
	v_bfe_u32 v27, v82, 16, 1
	v_lshrrev_b32_e32 v19, 16, v19
	v_add3_u32 v27, v82, v27, s46
	v_and_or_b32 v67, v27, s47, v19
	v_bfe_u32 v19, v71, 16, 1
	v_lshlrev_b32_e32 v84, 1, v8
	v_mov_b32_e32 v85, v3
	v_add3_u32 v19, v71, v19, s46
	v_bfe_u32 v27, v69, 16, 1
	v_lshl_add_u64 v[84:85], v[96:97], 0, v[84:85]
	v_lshrrev_b32_e32 v19, 16, v19
	v_add3_u32 v27, v69, v27, s46
	global_store_dwordx4 v[84:85], v[64:67], off nt
	v_lshlrev_b32_e32 v68, 1, v10
	v_mov_b32_e32 v69, v3
	v_and_or_b32 v64, v27, s47, v19
	v_bfe_u32 v19, v73, 16, 1
	v_add3_u32 v19, v73, v19, s46
	v_bfe_u32 v27, v75, 16, 1
	v_lshrrev_b32_e32 v19, 16, v19
	v_add3_u32 v27, v75, v27, s46
	v_and_or_b32 v65, v27, s47, v19
	v_bfe_u32 v19, v77, 16, 1
	v_add3_u32 v19, v77, v19, s46
	v_bfe_u32 v27, v79, 16, 1
	v_lshrrev_b32_e32 v19, 16, v19
	v_add3_u32 v27, v79, v27, s46
	v_and_or_b32 v66, v27, s47, v19
	v_bfe_u32 v19, v81, 16, 1
	v_add3_u32 v19, v81, v19, s46
	v_bfe_u32 v27, v83, 16, 1
	v_lshrrev_b32_e32 v19, 16, v19
	v_add3_u32 v27, v83, v27, s46
	v_and_or_b32 v67, v27, s47, v19
	v_lshl_add_u64 v[68:69], v[96:97], 0, v[68:69]
	global_store_dwordx4 v[68:69], v[64:67], off nt
	s_waitcnt lgkmcnt(0)
.LBB0_30:
	s_andn2_b64 vcc, exec, s[20:21]
	s_cbranch_vccnz .LBB0_32
	s_mov_b64 s[20:21], s[0:1]
	s_load_dwordx2 s[20:21], s[20:21], 0x58
	s_mov_b64 s[58:59], s[0:1]
	s_load_dwordx2 s[58:59], s[58:59], 0xc0
	s_lshl_b64 s[60:61], s[18:19], 21
	s_waitcnt lgkmcnt(0)
	s_add_u32 s4, s20, s60
	s_addc_u32 s20, s21, s61
	v_mov_b32_e32 v59, v3
	s_add_u32 s57, s58, s60
	s_addc_u32 s58, s59, s61
	s_and_b32 s59, s23, 0x1c0
	s_and_b32 s60, s27, 0x3e0
	s_lshl_b32 s21, s59, 12
	s_add_u32 s4, s4, s21
	s_addc_u32 s21, s20, 0
	s_lshl_b32 s20, s60, 2
	s_add_u32 s20, s4, s20
	s_addc_u32 s21, s21, 0
	v_lshl_add_u64 v[92:93], s[20:21], 0, v[2:3]
	v_mov_b32_e32 v61, v3
	v_mov_b32_e32 v63, v3
	v_lshlrev_b32_e32 v74, 2, v10
	v_mov_b32_e32 v75, v3
	v_lshlrev_b32_e32 v80, 2, v12
	v_mov_b32_e32 v81, v3
	v_lshlrev_b32_e32 v82, 2, v14
	v_mov_b32_e32 v83, v3
	v_lshl_add_u64 v[64:65], v[92:93], 0, v[58:59]
	v_lshl_add_u64 v[68:69], v[92:93], 0, v[60:61]
	v_lshl_add_u64 v[72:73], v[92:93], 0, v[62:63]
	v_lshl_add_u64 v[76:77], v[92:93], 0, v[74:75]
	v_lshl_add_u64 v[80:81], v[92:93], 0, v[80:81]
	v_lshl_add_u64 v[84:85], v[92:93], 0, v[82:83]
	global_load_dwordx4 v[64:67], v[64:65], off nt
	s_nop 0
	global_load_dwordx4 v[68:71], v[68:69], off nt
	s_nop 0
	global_load_dwordx4 v[72:75], v[72:73], off nt
	s_nop 0
	global_load_dwordx4 v[76:79], v[76:77], off nt
	s_nop 0
	global_load_dwordx4 v[80:83], v[80:81], off nt
	s_nop 0
	global_load_dwordx4 v[84:87], v[84:85], off nt
	v_lshlrev_b32_e32 v88, 2, v16
	v_mov_b32_e32 v89, v3
	v_lshl_add_u64 v[88:89], v[92:93], 0, v[88:89]
	global_load_dwordx4 v[88:91], v[88:89], off nt
	v_lshlrev_b32_e32 v94, 2, v18
	v_mov_b32_e32 v95, v3
	v_lshl_add_u64 v[92:93], v[92:93], 0, v[94:95]
	global_load_dwordx4 v[92:95], v[92:93], off nt
	v_add_u32_e32 v19, v13, v15
	v_add_u32_e32 v27, 0x420, v19
	v_add_u32_e32 v29, 0x428, v19
	v_add_u32_e32 v31, 0x840, v19
	v_add_u32_e32 v33, 0x848, v19
	v_add_u32_e32 v35, 0xc60, v19
	v_add_u32_e32 v37, 0xc68, v19
	v_add_u32_e32 v39, 0x1080, v19
	v_add_u32_e32 v41, 0x1088, v19
	v_add_u32_e32 v43, 0x14a0, v19
	v_add_u32_e32 v45, 0x14a8, v19
	v_add_u32_e32 v47, 0x18c0, v19
	v_add_u32_e32 v49, 0x18c8, v19
	v_add_u32_e32 v51, 0x1ce0, v19
	v_add_u32_e32 v53, 0x1ce8, v19
	s_lshl_b32 s4, s60, 10
	s_add_u32 s4, s57, s4
	s_addc_u32 s21, s58, 0
	s_lshl_b32 s20, s59, 1
	s_add_u32 s20, s4, s20
	v_lshlrev_b32_e32 v96, 1, v20
	v_mov_b32_e32 v97, v3
	s_addc_u32 s21, s21, 0
	v_lshl_add_u64 v[96:97], s[20:21], 0, v[96:97]
	v_lshl_add_u64 v[96:97], v[96:97], 0, s[12:13]
	s_waitcnt vmcnt(7)
; #define LAS __attribute__((address_space(3)))
; __device__ __forceinline__ unsigned pk2(float lo, float hi) { return f2bf(lo) | (f2bf(hi) << 16); }
; __device__ __forceinline__ void tr_block(const float* src  , int ldw, bf16* dst  , int K, LAS float* scr, int lane) {
;     ...
;     const int c = lane & 7;
; #pragma unroll
;     for (int j = 0; j < 4; ++j) { const int n = (lane >> 3) + 8 * j; const LAS float* s = scr + (8 * c) * 33 + n;
;         v4u o; o.x = pk2(s[0 * 33], s[1 * 33]); o.y = pk2(s[2 * 33], s[3 * 33]); o.z = pk2(s[4 * 33], s[5 * 33]); o.w = pk2(s[6 * 33], s[7 * 33]);
;         *(v4u*)(dst + (size_t)n * K + 8 * c) = o; }
;     asm volatile("s_waitcnt lgkmcnt(0)" ::: "memory");
	ds_write2_b32 v19, v64, v65 offset1:1
	ds_write2_b32 v19, v66, v67 offset0:2 offset1:3
	s_waitcnt vmcnt(6)
	ds_write2_b32 v27, v68, v69 offset1:1
	ds_write2_b32 v29, v70, v71 offset1:1
	s_waitcnt vmcnt(5)
	ds_write2_b32 v31, v72, v73 offset1:1
	ds_write2_b32 v33, v74, v75 offset1:1
	s_waitcnt vmcnt(4)
	ds_write2_b32 v35, v76, v77 offset1:1
	ds_write2_b32 v37, v78, v79 offset1:1
	s_waitcnt vmcnt(3)
	ds_write2_b32 v39, v80, v81 offset1:1
	ds_write2_b32 v41, v82, v83 offset1:1
	s_waitcnt vmcnt(2)
	ds_write2_b32 v43, v84, v85 offset1:1
	ds_write2_b32 v45, v86, v87 offset1:1
	s_waitcnt vmcnt(1)
	ds_write2_b32 v47, v88, v89 offset1:1
	ds_write2_b32 v49, v90, v91 offset1:1
	s_waitcnt vmcnt(0)
	ds_write2_b32 v51, v92, v93 offset1:1
	ds_write2_b32 v53, v94, v95 offset1:1
	s_waitcnt lgkmcnt(0)
	ds_read2_b32 v[68:69], v17 offset0:33 offset1:41
	ds_read2_b32 v[70:71], v17 offset1:8
	ds_read2_b32 v[72:73], v17 offset0:66 offset1:74
	ds_read2_b32 v[74:75], v17 offset0:99 offset1:107
	ds_read2_b32 v[76:77], v17 offset0:132 offset1:140
	ds_read2_b32 v[78:79], v17 offset0:165 offset1:173
	s_waitcnt lgkmcnt(4)
	v_bfe_u32 v19, v70, 16, 1
	v_bfe_u32 v27, v68, 16, 1
	v_add3_u32 v19, v70, v19, s46
	ds_read2_b32 v[80:81], v17 offset0:198 offset1:206
	v_add3_u32 v27, v68, v27, s46
	v_lshrrev_b32_e32 v19, 16, v19
	ds_read2_b32 v[82:83], v17 offset0:231 offset1:239
	v_and_or_b32 v64, v27, s47, v19
	s_waitcnt lgkmcnt(3)
	v_bfe_u32 v19, v76, 16, 1
	v_add3_u32 v19, v76, v19, s46
	s_waitcnt lgkmcnt(2)
	v_bfe_u32 v27, v78, 16, 1
	v_lshrrev_b32_e32 v19, 16, v19
	v_add3_u32 v27, v78, v27, s46
	v_and_or_b32 v66, v27, s47, v19
	s_waitcnt lgkmcnt(1)
	v_bfe_u32 v19, v80, 16, 1
	v_add3_u32 v19, v80, v19, s46
	s_waitcnt lgkmcnt(0)
	v_bfe_u32 v27, v82, 16, 1
	v_bfe_u32 v29, v72, 16, 1
	v_lshrrev_b32_e32 v19, 16, v19
	v_add3_u32 v27, v82, v27, s46
	v_bfe_u32 v31, v74, 16, 1
	v_add3_u32 v29, v72, v29, s46
	v_and_or_b32 v67, v27, s47, v19
	v_bfe_u32 v19, v71, 16, 1
	v_add3_u32 v31, v74, v31, s46
	v_lshrrev_b32_e32 v29, 16, v29
	v_lshlrev_b32_e32 v84, 1, v26
	v_mov_b32_e32 v85, v3
	v_add3_u32 v19, v71, v19, s46
	v_bfe_u32 v27, v69, 16, 1
	v_and_or_b32 v65, v31, s47, v29
	v_lshl_add_u64 v[84:85], v[96:97], 0, v[84:85]
	v_lshrrev_b32_e32 v19, 16, v19
	v_add3_u32 v27, v69, v27, s46
	global_store_dwordx4 v[84:85], v[64:67], off nt
	v_lshlrev_b32_e32 v68, 1, v28
	v_mov_b32_e32 v69, v3
	v_and_or_b32 v64, v27, s47, v19
	v_bfe_u32 v19, v73, 16, 1
	v_add3_u32 v19, v73, v19, s46
	v_bfe_u32 v27, v75, 16, 1
	v_lshrrev_b32_e32 v19, 16, v19
	v_add3_u32 v27, v75, v27, s46
	v_and_or_b32 v65, v27, s47, v19
	v_bfe_u32 v19, v77, 16, 1
	v_add3_u32 v19, v77, v19, s46
	v_bfe_u32 v27, v79, 16, 1
	v_lshrrev_b32_e32 v19, 16, v19
	v_add3_u32 v27, v79, v27, s46
	v_and_or_b32 v66, v27, s47, v19
	v_bfe_u32 v19, v81, 16, 1
	v_add3_u32 v19, v81, v19, s46
	v_bfe_u32 v27, v83, 16, 1
	v_lshrrev_b32_e32 v19, 16, v19
	v_add3_u32 v27, v83, v27, s46
	v_and_or_b32 v67, v27, s47, v19
	ds_read2_b32 v[70:71], v17 offset0:16 offset1:24
	v_lshl_add_u64 v[68:69], v[96:97], 0, v[68:69]
	global_store_dwordx4 v[68:69], v[64:67], off nt
	ds_read2_b32 v[68:69], v17 offset0:49 offset1:57
	ds_read2_b32 v[72:73], v17 offset0:82 offset1:90
	ds_read2_b32 v[74:75], v17 offset0:115 offset1:123
	s_waitcnt lgkmcnt(3)
	v_bfe_u32 v19, v70, 16, 1
	v_add3_u32 v19, v70, v19, s46
	s_waitcnt lgkmcnt(2)
	v_bfe_u32 v27, v68, 16, 1
	ds_read2_b32 v[76:77], v17 offset0:148 offset1:156
	v_lshrrev_b32_e32 v19, 16, v19
	v_add3_u32 v27, v68, v27, s46
	ds_read2_b32 v[78:79], v17 offset0:181 offset1:189
	v_and_or_b32 v64, v27, s47, v19
	s_waitcnt lgkmcnt(3)
	v_bfe_u32 v19, v72, 16, 1
	v_add3_u32 v19, v72, v19, s46
	s_waitcnt lgkmcnt(2)
	v_bfe_u32 v27, v74, 16, 1
	ds_read2_b32 v[80:81], v17 offset0:214 offset1:222
	v_lshrrev_b32_e32 v19, 16, v19
	v_add3_u32 v27, v74, v27, s46
	ds_read2_b32 v[82:83], v17 offset0:247 offset1:255
	v_and_or_b32 v65, v27, s47, v19
	s_waitcnt lgkmcnt(3)
	v_bfe_u32 v19, v76, 16, 1
	v_add3_u32 v19, v76, v19, s46
	s_waitcnt lgkmcnt(2)
	v_bfe_u32 v27, v78, 16, 1
	v_lshrrev_b32_e32 v19, 16, v19
	v_add3_u32 v27, v78, v27, s46
	v_and_or_b32 v66, v27, s47, v19
	s_waitcnt lgkmcnt(1)
	v_bfe_u32 v19, v80, 16, 1
	v_add3_u32 v19, v80, v19, s46
	s_waitcnt lgkmcnt(0)
	v_bfe_u32 v27, v82, 16, 1
	v_lshrrev_b32_e32 v19, 16, v19
	v_add3_u32 v27, v82, v27, s46
	v_and_or_b32 v67, v27, s47, v19
	v_bfe_u32 v19, v71, 16, 1
	v_lshlrev_b32_e32 v84, 1, v30
	v_mov_b32_e32 v85, v3
	v_add3_u32 v19, v71, v19, s46
	v_bfe_u32 v27, v69, 16, 1
	v_lshl_add_u64 v[84:85], v[96:97], 0, v[84:85]
	v_lshrrev_b32_e32 v19, 16, v19
	v_add3_u32 v27, v69, v27, s46
	global_store_dwordx4 v[84:85], v[64:67], off nt
	v_lshlrev_b32_e32 v68, 1, v32
	v_mov_b32_e32 v69, v3
	v_and_or_b32 v64, v27, s47, v19
	v_bfe_u32 v19, v73, 16, 1
	v_add3_u32 v19, v73, v19, s46
	v_bfe_u32 v27, v75, 16, 1
	v_lshrrev_b32_e32 v19, 16, v19
	v_add3_u32 v27, v75, v27, s46
	v_and_or_b32 v65, v27, s47, v19
	v_bfe_u32 v19, v77, 16, 1
	v_add3_u32 v19, v77, v19, s46
	v_bfe_u32 v27, v79, 16, 1
	v_lshrrev_b32_e32 v19, 16, v19
	v_add3_u32 v27, v79, v27, s46
	v_and_or_b32 v66, v27, s47, v19
	v_bfe_u32 v19, v81, 16, 1
	v_add3_u32 v19, v81, v19, s46
	v_bfe_u32 v27, v83, 16, 1
	v_lshrrev_b32_e32 v19, 16, v19
	v_add3_u32 v27, v83, v27, s46
	v_and_or_b32 v67, v27, s47, v19
	v_lshl_add_u64 v[68:69], v[96:97], 0, v[68:69]
	global_store_dwordx4 v[68:69], v[64:67], off nt
	s_waitcnt lgkmcnt(0)

; #define LAS __attribute__((address_space(3)))
; __device__ __forceinline__ unsigned pk2(float lo, float hi) { return f2bf(lo) | (f2bf(hi) << 16); }
; #define in KArgIn()
; __device__ __forceinline__ void tr_block(const float* src  , int ldw, bf16* dst  , int K, LAS float* scr, int lane) {
;     const int kr = lane >> 3, c4 = lane & 7;
;     f32x4 v[8];
; #pragma unroll
;     for (int i = 0; i < 8; ++i) v[i] = *(const f32x4*)(src + (size_t)(8 * i + kr) * ldw + 4 * c4);
; #pragma unroll
;     for (int i = 0; i < 8; ++i) { LAS float* d = scr + (8 * i + kr) * 33 + 4 * c4; d[0] = v[i].x; d[1] = v[i].y; d[2] = v[i].z; d[3] = v[i].w; }
;     asm volatile("s_waitcnt lgkmcnt(0)" ::: "memory");
;     const int c = lane & 7;
; #pragma unroll
;     for (int j = 0; j < 4; ++j) { const int n = (lane >> 3) + 8 * j; const LAS float* s = scr + (8 * c) * 33 + n;
;         v4u o; o.x = pk2(s[0 * 33], s[1 * 33]); o.y = pk2(s[2 * 33], s[3 * 33]); o.z = pk2(s[4 * 33], s[5 * 33]); o.w = pk2(s[6 * 33], s[7 * 33]);
;         *(v4u*)(dst + (size_t)n * K + 8 * c) = o; }
;     asm volatile("s_waitcnt lgkmcnt(0)" ::: "memory");
; template <int SEL> __global__ void __launch_bounds__(NWAVES * 64, 2) fwd_kernel(Args args) {
;     ...
;                 if (r < I_BR) { tr_seg<0>(in[10] + (size_t)l * 512 * 1024, 1024, 512, 0, 1024, q_Wbr_t + (size_t)l * 2048 * 512, 0, 0, scr, r, lane); continue; } r -= I_BR;
.LBB0_33:
	s_andn2_b64 vcc, exec, s[20:21]
	s_cbranch_vccnz .LBB0_35
	s_mov_b64 s[20:21], s[0:1]
	s_load_dwordx2 s[20:21], s[20:21], 0x50
	s_mov_b64 s[58:59], s[0:1]
	s_load_dwordx2 s[58:59], s[58:59], 0xc0
	s_lshl_b64 s[18:19], s[18:19], 21
	s_waitcnt lgkmcnt(0)
	s_add_u32 s4, s20, s18
	s_addc_u32 s20, s21, s19
	v_mov_b32_e32 v59, v3
	s_add_u32 s21, s58, s18
	s_addc_u32 s57, s59, s19
	s_and_b32 s58, s23, 0x1c0
	s_and_b32 s59, s27, 0x3e0
	s_lshl_b32 s18, s58, 12
	s_add_u32 s4, s4, s18
	s_addc_u32 s19, s20, 0
	s_lshl_b32 s18, s59, 2
	s_add_u32 s18, s4, s18
	s_addc_u32 s19, s19, 0
	v_lshl_add_u64 v[92:93], s[18:19], 0, v[2:3]
	v_mov_b32_e32 v61, v3
	v_mov_b32_e32 v63, v3
	v_lshlrev_b32_e32 v74, 2, v10
	v_mov_b32_e32 v75, v3
	v_lshlrev_b32_e32 v80, 2, v12
	v_mov_b32_e32 v81, v3
	v_lshlrev_b32_e32 v82, 2, v14
	v_mov_b32_e32 v83, v3
	v_lshl_add_u64 v[64:65], v[92:93], 0, v[58:59]
	v_lshl_add_u64 v[68:69], v[92:93], 0, v[60:61]
	v_lshl_add_u64 v[72:73], v[92:93], 0, v[62:63]
	v_lshl_add_u64 v[76:77], v[92:93], 0, v[74:75]
	v_lshl_add_u64 v[80:81], v[92:93], 0, v[80:81]
	v_lshl_add_u64 v[84:85], v[92:93], 0, v[82:83]
	global_load_dwordx4 v[64:67], v[64:65], off nt
	s_nop 0
	global_load_dwordx4 v[68:71], v[68:69], off nt
	s_nop 0
	global_load_dwordx4 v[72:75], v[72:73], off nt
	s_nop 0
	global_load_dwordx4 v[76:79], v[76:77], off nt
	s_nop 0
	global_load_dwordx4 v[80:83], v[80:81], off nt
	s_nop 0
	global_load_dwordx4 v[84:87], v[84:85], off nt
	v_lshlrev_b32_e32 v88, 2, v16
	v_mov_b32_e32 v89, v3
	v_lshl_add_u64 v[88:89], v[92:93], 0, v[88:89]
	global_load_dwordx4 v[88:91], v[88:89], off nt
	v_lshlrev_b32_e32 v94, 2, v18
	v_mov_b32_e32 v95, v3
	v_lshl_add_u64 v[92:93], v[92:93], 0, v[94:95]
	global_load_dwordx4 v[92:95], v[92:93], off nt
	v_add_u32_e32 v19, v13, v15
	v_add_u32_e32 v27, 0x420, v19
	v_add_u32_e32 v29, 0x428, v19
	v_add_u32_e32 v31, 0x840, v19
	v_add_u32_e32 v33, 0x848, v19
	v_add_u32_e32 v35, 0xc60, v19
	v_add_u32_e32 v37, 0xc68, v19
	v_add_u32_e32 v39, 0x1080, v19
	v_add_u32_e32 v41, 0x1088, v19
	v_add_u32_e32 v43, 0x14a0, v19
	v_add_u32_e32 v45, 0x14a8, v19
	v_add_u32_e32 v47, 0x18c0, v19
	v_add_u32_e32 v49, 0x18c8, v19
	v_add_u32_e32 v51, 0x1ce0, v19
	v_add_u32_e32 v53, 0x1ce8, v19
	s_lshl_b32 s4, s59, 10
	s_add_u32 s4, s21, s4
	s_addc_u32 s19, s57, 0
	s_lshl_b32 s18, s58, 1
	s_add_u32 s18, s4, s18
	v_lshlrev_b32_e32 v96, 1, v20
	v_mov_b32_e32 v97, v3
	s_addc_u32 s19, s19, 0
	v_lshl_add_u64 v[96:97], s[18:19], 0, v[96:97]
	v_lshl_add_u64 v[96:97], v[96:97], 0, s[14:15]
	s_waitcnt vmcnt(7)
	ds_write2_b32 v19, v64, v65 offset1:1
	ds_write2_b32 v19, v66, v67 offset0:2 offset1:3
	s_waitcnt vmcnt(6)
	ds_write2_b32 v27, v68, v69 offset1:1
	ds_write2_b32 v29, v70, v71 offset1:1
	s_waitcnt vmcnt(5)
	ds_write2_b32 v31, v72, v73 offset1:1
	ds_write2_b32 v33, v74, v75 offset1:1
	s_waitcnt vmcnt(4)
	ds_write2_b32 v35, v76, v77 offset1:1
	ds_write2_b32 v37, v78, v79 offset1:1
	s_waitcnt vmcnt(3)
	ds_write2_b32 v39, v80, v81 offset1:1
	ds_write2_b32 v41, v82, v83 offset1:1
	s_waitcnt vmcnt(2)
	ds_write2_b32 v43, v84, v85 offset1:1
	ds_write2_b32 v45, v86, v87 offset1:1
	s_waitcnt vmcnt(1)
	ds_write2_b32 v47, v88, v89 offset1:1
	ds_write2_b32 v49, v90, v91 offset1:1
	s_waitcnt vmcnt(0)
	ds_write2_b32 v51, v92, v93 offset1:1
	ds_write2_b32 v53, v94, v95 offset1:1
	s_waitcnt lgkmcnt(0)
	ds_read2_b32 v[68:69], v17 offset0:33 offset1:41
	ds_read2_b32 v[70:71], v17 offset1:8
	ds_read2_b32 v[72:73], v17 offset0:66 offset1:74
	ds_read2_b32 v[74:75], v17 offset0:99 offset1:107
	ds_read2_b32 v[76:77], v17 offset0:132 offset1:140
	ds_read2_b32 v[78:79], v17 offset0:165 offset1:173
	s_waitcnt lgkmcnt(4)
	v_bfe_u32 v19, v70, 16, 1
	v_bfe_u32 v27, v68, 16, 1
	v_add3_u32 v19, v70, v19, s46
	ds_read2_b32 v[80:81], v17 offset0:198 offset1:206
	v_add3_u32 v27, v68, v27, s46
	v_lshrrev_b32_e32 v19, 16, v19
	ds_read2_b32 v[82:83], v17 offset0:231 offset1:239
	v_and_or_b32 v64, v27, s47, v19
	s_waitcnt lgkmcnt(3)
; #define LAS __attribute__((address_space(3)))
; __device__ __forceinline__ unsigned pk2(float lo, float hi) { return f2bf(lo) | (f2bf(hi) << 16); }
; __device__ __forceinline__ void tr_block(const float* src  , int ldw, bf16* dst  , int K, LAS float* scr, int lane) {
;     ...
;     const int c = lane & 7;
; #pragma unroll
;     for (int j = 0; j < 4; ++j) { const int n = (lane >> 3) + 8 * j; const LAS float* s = scr + (8 * c) * 33 + n;
;         v4u o; o.x = pk2(s[0 * 33], s[1 * 33]); o.y = pk2(s[2 * 33], s[3 * 33]); o.z = pk2(s[4 * 33], s[5 * 33]); o.w = pk2(s[6 * 33], s[7 * 33]);
;         *(v4u*)(dst + (size_t)n * K + 8 * c) = o; }
;     asm volatile("s_waitcnt lgkmcnt(0)" ::: "memory");
	v_bfe_u32 v19, v76, 16, 1
	v_add3_u32 v19, v76, v19, s46
	s_waitcnt lgkmcnt(2)
	v_bfe_u32 v27, v78, 16, 1
	v_lshrrev_b32_e32 v19, 16, v19
	v_add3_u32 v27, v78, v27, s46
	v_and_or_b32 v66, v27, s47, v19
	s_waitcnt lgkmcnt(1)
	v_bfe_u32 v19, v80, 16, 1
	v_add3_u32 v19, v80, v19, s46
	s_waitcnt lgkmcnt(0)
	v_bfe_u32 v27, v82, 16, 1
	v_bfe_u32 v29, v72, 16, 1
	v_lshrrev_b32_e32 v19, 16, v19
	v_add3_u32 v27, v82, v27, s46
	v_bfe_u32 v31, v74, 16, 1
	v_add3_u32 v29, v72, v29, s46
	v_and_or_b32 v67, v27, s47, v19
	v_bfe_u32 v19, v71, 16, 1
	v_add3_u32 v31, v74, v31, s46
	v_lshrrev_b32_e32 v29, 16, v29
	v_lshlrev_b32_e32 v84, 1, v26
	v_mov_b32_e32 v85, v3
	v_add3_u32 v19, v71, v19, s46
	v_bfe_u32 v27, v69, 16, 1
	v_and_or_b32 v65, v31, s47, v29
	v_lshl_add_u64 v[84:85], v[96:97], 0, v[84:85]
	v_lshrrev_b32_e32 v19, 16, v19
	v_add3_u32 v27, v69, v27, s46
	global_store_dwordx4 v[84:85], v[64:67], off nt
	v_lshlrev_b32_e32 v68, 1, v28
	v_mov_b32_e32 v69, v3
	v_and_or_b32 v64, v27, s47, v19
	v_bfe_u32 v19, v73, 16, 1
	v_add3_u32 v19, v73, v19, s46
	v_bfe_u32 v27, v75, 16, 1
	v_lshrrev_b32_e32 v19, 16, v19
	v_add3_u32 v27, v75, v27, s46
	v_and_or_b32 v65, v27, s47, v19
	v_bfe_u32 v19, v77, 16, 1
	v_add3_u32 v19, v77, v19, s46
	v_bfe_u32 v27, v79, 16, 1
	v_lshrrev_b32_e32 v19, 16, v19
	v_add3_u32 v27, v79, v27, s46
	v_and_or_b32 v66, v27, s47, v19
	v_bfe_u32 v19, v81, 16, 1
	v_add3_u32 v19, v81, v19, s46
	v_bfe_u32 v27, v83, 16, 1
	v_lshrrev_b32_e32 v19, 16, v19
	v_add3_u32 v27, v83, v27, s46
	v_and_or_b32 v67, v27, s47, v19
	ds_read2_b32 v[70:71], v17 offset0:16 offset1:24
	v_lshl_add_u64 v[68:69], v[96:97], 0, v[68:69]
	global_store_dwordx4 v[68:69], v[64:67], off nt
	ds_read2_b32 v[68:69], v17 offset0:49 offset1:57
	ds_read2_b32 v[72:73], v17 offset0:82 offset1:90
	ds_read2_b32 v[74:75], v17 offset0:115 offset1:123
	s_waitcnt lgkmcnt(3)
	v_bfe_u32 v19, v70, 16, 1
	v_add3_u32 v19, v70, v19, s46
	s_waitcnt lgkmcnt(2)
	v_bfe_u32 v27, v68, 16, 1
	ds_read2_b32 v[76:77], v17 offset0:148 offset1:156
	v_lshrrev_b32_e32 v19, 16, v19
	v_add3_u32 v27, v68, v27, s46
	ds_read2_b32 v[78:79], v17 offset0:181 offset1:189
	v_and_or_b32 v64, v27, s47, v19
	s_waitcnt lgkmcnt(3)
	v_bfe_u32 v19, v72, 16, 1
	v_add3_u32 v19, v72, v19, s46
	s_waitcnt lgkmcnt(2)
	v_bfe_u32 v27, v74, 16, 1
	ds_read2_b32 v[80:81], v17 offset0:214 offset1:222
	v_lshrrev_b32_e32 v19, 16, v19
	v_add3_u32 v27, v74, v27, s46
	ds_read2_b32 v[82:83], v17 offset0:247 offset1:255
	v_and_or_b32 v65, v27, s47, v19
	s_waitcnt lgkmcnt(3)
	v_bfe_u32 v19, v76, 16, 1
	v_add3_u32 v19, v76, v19, s46
	s_waitcnt lgkmcnt(2)
	v_bfe_u32 v27, v78, 16, 1
	v_lshrrev_b32_e32 v19, 16, v19
	v_add3_u32 v27, v78, v27, s46
	v_and_or_b32 v66, v27, s47, v19
	s_waitcnt lgkmcnt(1)
	v_bfe_u32 v19, v80, 16, 1
	v_add3_u32 v19, v80, v19, s46
	s_waitcnt lgkmcnt(0)
	v_bfe_u32 v27, v82, 16, 1
	v_lshrrev_b32_e32 v19, 16, v19
	v_add3_u32 v27, v82, v27, s46
	v_and_or_b32 v67, v27, s47, v19
	v_bfe_u32 v19, v71, 16, 1
	v_lshlrev_b32_e32 v84, 1, v30
	v_mov_b32_e32 v85, v3
	v_add3_u32 v19, v71, v19, s46
	v_bfe_u32 v27, v69, 16, 1
	v_lshl_add_u64 v[84:85], v[96:97], 0, v[84:85]
	v_lshrrev_b32_e32 v19, 16, v19
	v_add3_u32 v27, v69, v27, s46
	global_store_dwordx4 v[84:85], v[64:67], off nt
	v_lshlrev_b32_e32 v68, 1, v32
	v_mov_b32_e32 v69, v3
	v_and_or_b32 v64, v27, s47, v19
	v_bfe_u32 v19, v73, 16, 1
	v_add3_u32 v19, v73, v19, s46
	v_bfe_u32 v27, v75, 16, 1
	v_lshrrev_b32_e32 v19, 16, v19
	v_add3_u32 v27, v75, v27, s46
	v_and_or_b32 v65, v27, s47, v19
	v_bfe_u32 v19, v77, 16, 1
	v_add3_u32 v19, v77, v19, s46
	v_bfe_u32 v27, v79, 16, 1
	v_lshrrev_b32_e32 v19, 16, v19
	v_add3_u32 v27, v79, v27, s46
	v_and_or_b32 v66, v27, s47, v19
	v_bfe_u32 v19, v81, 16, 1
	v_add3_u32 v19, v81, v19, s46
	v_bfe_u32 v27, v83, 16, 1
	v_lshrrev_b32_e32 v19, 16, v19
	v_add3_u32 v27, v83, v27, s46
	v_and_or_b32 v67, v27, s47, v19
	v_lshl_add_u64 v[68:69], v[96:97], 0, v[68:69]
	global_store_dwordx4 v[68:69], v[64:67], off nt
	s_waitcnt lgkmcnt(0)

; #define LAS __attribute__((address_space(3)))
; __device__ __forceinline__ unsigned pk2(float lo, float hi) { return f2bf(lo) | (f2bf(hi) << 16); }
; __device__ __forceinline__ void tr_block(const float* src  , int ldw, bf16* dst  , int K, LAS float* scr, int lane) {
;     const int kr = lane >> 3, c4 = lane & 7;
;     f32x4 v[8];
; #pragma unroll
;     for (int i = 0; i < 8; ++i) v[i] = *(const f32x4*)(src + (size_t)(8 * i + kr) * ldw + 4 * c4);
; #pragma unroll
;     for (int i = 0; i < 8; ++i) { LAS float* d = scr + (8 * i + kr) * 33 + 4 * c4; d[0] = v[i].x; d[1] = v[i].y; d[2] = v[i].z; d[3] = v[i].w; }
;     asm volatile("s_waitcnt lgkmcnt(0)" ::: "memory");
;     const int c = lane & 7;
; #pragma unroll
;     for (int j = 0; j < 4; ++j) { const int n = (lane >> 3) + 8 * j; const LAS float* s = scr + (8 * c) * 33 + n;
;         v4u o; o.x = pk2(s[0 * 33], s[1 * 33]); o.y = pk2(s[2 * 33], s[3 * 33]); o.z = pk2(s[4 * 33], s[5 * 33]); o.w = pk2(s[6 * 33], s[7 * 33]);
;         *(v4u*)(dst + (size_t)n * K + 8 * c) = o; }
;     asm volatile("s_waitcnt lgkmcnt(0)" ::: "memory");
; template <int SEL> __global__ void __launch_bounds__(NWAVES * 64, 2) fwd_kernel(Args args) {
;     ...
;                 if (r < I_B) { tr_seg<0>(win, NIN, 1024, 1544, 3584, wt, 1536, 0, scr, r, lane); continue; } r -= I_B;
.LBB0_36:
	s_andn2_b64 vcc, exec, s[20:21]
	s_cbranch_vccnz .LBB0_38
	s_add_i32 s4, s54, 0xfd00
	s_bfe_u32 s18, s4, 0xc0004
	s_mulk_i32 s18, 0x2493
	s_lshr_b32 s20, s18, 16
	s_mul_i32 s18, s20, 0x70
	s_sub_i32 s4, s4, s18
	s_lshl_b32 s18, s4, 5
	s_add_i32 s21, s18, 0x600
	s_mul_i32 s18, s20, 0x140800
	s_add_u32 s18, s55, s18
	s_addc_u32 s19, s56, 0
	s_lshl_b32 s4, s4, 7
	s_and_b32 s4, s4, 0x3ff80
	s_add_u32 s18, s18, s4
	s_addc_u32 s19, s19, 0
	v_lshl_add_u64 v[64:65], s[18:19], 0, v[2:3]
	v_lshl_add_u64 v[80:81], v[64:65], 0, s[16:17]
	v_lshlrev_b32_e32 v64, 2, v34
	v_mov_b32_e32 v65, v3
	v_lshl_add_u64 v[92:93], v[80:81], 0, v[64:65]
	v_add_co_u32_e32 v68, vcc, s48, v92
	v_lshlrev_b32_e32 v72, 2, v36
	s_nop 0
	v_addc_co_u32_e32 v69, vcc, 0, v93, vcc
	v_add_co_u32_e32 v84, vcc, s49, v92
	v_mov_b32_e32 v73, v3
	s_nop 0
	v_addc_co_u32_e32 v85, vcc, 0, v93, vcc
	v_lshlrev_b32_e32 v74, 2, v38
	v_mov_b32_e32 v75, v3
	v_lshlrev_b32_e32 v82, 2, v40
	v_mov_b32_e32 v83, v3
	v_add_co_u32_e32 v88, vcc, s50, v92
	v_lshl_add_u64 v[72:73], v[80:81], 0, v[72:73]
	v_lshl_add_u64 v[76:77], v[80:81], 0, v[74:75]
	v_lshl_add_u64 v[80:81], v[80:81], 0, v[82:83]
	v_addc_co_u32_e32 v89, vcc, 0, v93, vcc
	global_load_dwordx4 v[64:67], v[92:93], off nt
	s_nop 0
	global_load_dwordx4 v[68:71], v[68:69], off offset:256
	s_nop 0
	global_load_dwordx4 v[72:75], v[72:73], off nt
	s_nop 0
	global_load_dwordx4 v[76:79], v[76:77], off nt
	v_add_co_u32_e32 v92, vcc, s51, v92
	global_load_dwordx4 v[80:83], v[80:81], off nt
	s_nop 0
	global_load_dwordx4 v[84:87], v[84:85], off offset:512
	s_nop 0
	global_load_dwordx4 v[88:91], v[88:89], off offset:768
	v_addc_co_u32_e32 v93, vcc, 0, v93, vcc
	global_load_dwordx4 v[92:95], v[92:93], off offset:1024
	v_add_u32_e32 v19, v13, v15
	v_add_u32_e32 v27, 0x420, v19
	v_add_u32_e32 v29, 0x428, v19
	v_add_u32_e32 v31, 0x840, v19
	v_add_u32_e32 v33, 0x848, v19
	v_add_u32_e32 v35, 0xc60, v19
	v_add_u32_e32 v37, 0xc68, v19
	v_add_u32_e32 v39, 0x1080, v19
	v_add_u32_e32 v41, 0x1088, v19
	v_add_u32_e32 v43, 0x14a0, v19
	v_add_u32_e32 v45, 0x14a8, v19
	v_add_u32_e32 v47, 0x18c0, v19
	v_add_u32_e32 v49, 0x18c8, v19
	v_add_u32_e32 v51, 0x1ce0, v19
	v_add_u32_e32 v53, 0x1ce8, v19
	s_and_b32 s4, s21, 0xffe0
	s_lshl_b32 s4, s4, 11
	s_add_u32 s4, s52, s4
	s_addc_u32 s19, s53, 0
	s_lshl_b32 s18, s20, 7
	s_add_u32 s18, s4, s18
	v_lshlrev_b32_e32 v96, 1, v20
	v_mov_b32_e32 v97, v3
	s_addc_u32 s19, s19, 0
	s_waitcnt vmcnt(7)
	ds_write2_b32 v19, v64, v65 offset1:1
	ds_write2_b32 v19, v66, v67 offset0:2 offset1:3
	s_waitcnt vmcnt(5)
	ds_write2_b32 v43, v72, v73 offset1:1
	ds_write2_b32 v45, v74, v75 offset1:1
	s_waitcnt vmcnt(4)
	ds_write2_b32 v47, v76, v77 offset1:1
	ds_write2_b32 v49, v78, v79 offset1:1
	s_waitcnt vmcnt(3)
	ds_write2_b32 v51, v80, v81 offset1:1
	ds_write2_b32 v53, v82, v83 offset1:1
	ds_write2_b32 v27, v68, v69 offset1:1
	ds_write2_b32 v29, v70, v71 offset1:1
	s_waitcnt vmcnt(2)
	ds_write2_b32 v31, v84, v85 offset1:1
	ds_write2_b32 v33, v86, v87 offset1:1
	s_waitcnt vmcnt(1)
	ds_write2_b32 v35, v88, v89 offset1:1
	ds_write2_b32 v37, v90, v91 offset1:1
	s_waitcnt vmcnt(0)
	ds_write2_b32 v39, v92, v93 offset1:1
	ds_write2_b32 v41, v94, v95 offset1:1
	s_waitcnt lgkmcnt(0)
	ds_read2_b32 v[68:69], v17 offset1:8
	ds_read2_b32 v[70:71], v17 offset0:33 offset1:41
	ds_read2_b32 v[72:73], v17 offset0:66 offset1:74
	ds_read2_b32 v[76:77], v17 offset0:99 offset1:107
	ds_read2_b32 v[78:79], v17 offset0:132 offset1:140
	s_waitcnt lgkmcnt(4)
	v_bfe_u32 v19, v68, 16, 1
	s_waitcnt lgkmcnt(3)
	v_bfe_u32 v27, v70, 16, 1
	v_add3_u32 v19, v68, v19, s46
	ds_read2_b32 v[80:81], v17 offset0:165 offset1:173
	s_waitcnt lgkmcnt(3)
	v_bfe_u32 v29, v72, 16, 1
	v_add3_u32 v27, v70, v27, s46
	v_lshrrev_b32_e32 v19, 16, v19
	v_add3_u32 v29, v72, v29, s46
	v_and_or_b32 v64, v27, s47, v19
	s_waitcnt lgkmcnt(2)
	v_bfe_u32 v19, v76, 16, 1
	ds_read2_b32 v[82:83], v17 offset0:198 offset1:206
	v_lshrrev_b32_e32 v29, 16, v29
	v_add3_u32 v19, v76, v19, s46
	ds_read2_b32 v[84:85], v17 offset0:231 offset1:239
	v_and_or_b32 v65, v19, s47, v29
	s_waitcnt lgkmcnt(3)
; #define LAS __attribute__((address_space(3)))
; __device__ __forceinline__ unsigned pk2(float lo, float hi) { return f2bf(lo) | (f2bf(hi) << 16); }
; __device__ __forceinline__ void tr_block(const float* src  , int ldw, bf16* dst  , int K, LAS float* scr, int lane) {
;     ...
;     const int c = lane & 7;
; #pragma unroll
;     for (int j = 0; j < 4; ++j) { const int n = (lane >> 3) + 8 * j; const LAS float* s = scr + (8 * c) * 33 + n;
;         v4u o; o.x = pk2(s[0 * 33], s[1 * 33]); o.y = pk2(s[2 * 33], s[3 * 33]); o.z = pk2(s[4 * 33], s[5 * 33]); o.w = pk2(s[6 * 33], s[7 * 33]);
;         *(v4u*)(dst + (size_t)n * K + 8 * c) = o; }
;     asm volatile("s_waitcnt lgkmcnt(0)" ::: "memory");
	v_bfe_u32 v19, v78, 16, 1
	v_add3_u32 v19, v78, v19, s46
	s_waitcnt lgkmcnt(2)
	v_bfe_u32 v27, v80, 16, 1
	v_lshrrev_b32_e32 v19, 16, v19
	v_add3_u32 v27, v80, v27, s46
	v_and_or_b32 v66, v27, s47, v19
	s_waitcnt lgkmcnt(1)
	v_bfe_u32 v19, v82, 16, 1
	v_add3_u32 v19, v82, v19, s46
	s_waitcnt lgkmcnt(0)
	v_bfe_u32 v27, v84, 16, 1
	v_lshrrev_b32_e32 v19, 16, v19
	v_add3_u32 v27, v84, v27, s46
	v_and_or_b32 v67, v27, s47, v19
	v_bfe_u32 v19, v69, 16, 1
	v_lshl_add_u64 v[74:75], s[18:19], 0, v[96:97]
	v_lshlrev_b32_e32 v86, 1, v4
	v_mov_b32_e32 v87, v3
	v_add3_u32 v19, v69, v19, s46
	v_bfe_u32 v27, v71, 16, 1
	v_lshl_add_u64 v[86:87], v[74:75], 0, v[86:87]
	v_lshrrev_b32_e32 v19, 16, v19
	v_add3_u32 v27, v71, v27, s46
	global_store_dwordx4 v[86:87], v[64:67], off nt
	v_lshlrev_b32_e32 v68, 1, v6
	v_mov_b32_e32 v69, v3
	v_and_or_b32 v64, v27, s47, v19
	v_bfe_u32 v19, v73, 16, 1
	v_add3_u32 v19, v73, v19, s46
	v_bfe_u32 v27, v77, 16, 1
	v_lshrrev_b32_e32 v19, 16, v19
	v_add3_u32 v27, v77, v27, s46
	v_and_or_b32 v65, v27, s47, v19
	v_bfe_u32 v19, v79, 16, 1
	v_add3_u32 v19, v79, v19, s46
	v_bfe_u32 v27, v81, 16, 1
	v_lshrrev_b32_e32 v19, 16, v19
	v_add3_u32 v27, v81, v27, s46
	v_and_or_b32 v66, v27, s47, v19
	v_bfe_u32 v19, v83, 16, 1
	v_add3_u32 v19, v83, v19, s46
	v_bfe_u32 v27, v85, 16, 1
	v_lshrrev_b32_e32 v19, 16, v19
	v_add3_u32 v27, v85, v27, s46
	v_and_or_b32 v67, v27, s47, v19
	ds_read2_b32 v[70:71], v17 offset0:16 offset1:24
	v_lshl_add_u64 v[68:69], v[74:75], 0, v[68:69]
	global_store_dwordx4 v[68:69], v[64:67], off nt
	ds_read2_b32 v[68:69], v17 offset0:49 offset1:57
	ds_read2_b32 v[72:73], v17 offset0:82 offset1:90
	ds_read2_b32 v[76:77], v17 offset0:115 offset1:123
	s_waitcnt lgkmcnt(3)
	v_bfe_u32 v19, v70, 16, 1
	v_add3_u32 v19, v70, v19, s46
	s_waitcnt lgkmcnt(2)
	v_bfe_u32 v27, v68, 16, 1
	ds_read2_b32 v[78:79], v17 offset0:148 offset1:156
	v_lshrrev_b32_e32 v19, 16, v19
	v_add3_u32 v27, v68, v27, s46
	ds_read2_b32 v[80:81], v17 offset0:181 offset1:189
	v_and_or_b32 v64, v27, s47, v19
	s_waitcnt lgkmcnt(3)
	v_bfe_u32 v19, v72, 16, 1
	v_add3_u32 v19, v72, v19, s46
	s_waitcnt lgkmcnt(2)
	v_bfe_u32 v27, v76, 16, 1
	ds_read2_b32 v[82:83], v17 offset0:214 offset1:222
	v_lshrrev_b32_e32 v19, 16, v19
	v_add3_u32 v27, v76, v27, s46
	ds_read2_b32 v[84:85], v17 offset0:247 offset1:255
	v_and_or_b32 v65, v27, s47, v19
	s_waitcnt lgkmcnt(3)
	v_bfe_u32 v19, v78, 16, 1
	v_add3_u32 v19, v78, v19, s46
	s_waitcnt lgkmcnt(2)
	v_bfe_u32 v27, v80, 16, 1
	v_lshrrev_b32_e32 v19, 16, v19
	v_add3_u32 v27, v80, v27, s46
	v_and_or_b32 v66, v27, s47, v19
	s_waitcnt lgkmcnt(1)
	v_bfe_u32 v19, v82, 16, 1
	v_add3_u32 v19, v82, v19, s46
	s_waitcnt lgkmcnt(0)
	v_bfe_u32 v27, v84, 16, 1
	v_lshrrev_b32_e32 v19, 16, v19
	v_add3_u32 v27, v84, v27, s46
	v_and_or_b32 v67, v27, s47, v19
	v_bfe_u32 v19, v71, 16, 1
	v_lshlrev_b32_e32 v86, 1, v8
	v_mov_b32_e32 v87, v3
	v_add3_u32 v19, v71, v19, s46
	v_bfe_u32 v27, v69, 16, 1
	v_lshl_add_u64 v[86:87], v[74:75], 0, v[86:87]
	v_lshrrev_b32_e32 v19, 16, v19
	v_add3_u32 v27, v69, v27, s46
	global_store_dwordx4 v[86:87], v[64:67], off nt
	v_lshlrev_b32_e32 v68, 1, v10
	v_mov_b32_e32 v69, v3
	v_and_or_b32 v64, v27, s47, v19
	v_bfe_u32 v19, v73, 16, 1
	v_add3_u32 v19, v73, v19, s46
	v_bfe_u32 v27, v77, 16, 1
	v_lshrrev_b32_e32 v19, 16, v19
	v_add3_u32 v27, v77, v27, s46
	v_and_or_b32 v65, v27, s47, v19
	v_bfe_u32 v19, v79, 16, 1
	v_add3_u32 v19, v79, v19, s46
	v_bfe_u32 v27, v81, 16, 1
	v_lshrrev_b32_e32 v19, 16, v19
	v_add3_u32 v27, v81, v27, s46
	v_and_or_b32 v66, v27, s47, v19
	v_bfe_u32 v19, v83, 16, 1
	v_add3_u32 v19, v83, v19, s46
	v_bfe_u32 v27, v85, 16, 1
	v_lshrrev_b32_e32 v19, 16, v19
	v_add3_u32 v27, v85, v27, s46
	v_and_or_b32 v67, v27, s47, v19
	v_lshl_add_u64 v[68:69], v[74:75], 0, v[68:69]
	global_store_dwordx4 v[68:69], v[64:67], off nt
	s_waitcnt lgkmcnt(0)

; #define LAS __attribute__((address_space(3)))
; __device__ __forceinline__ unsigned pk2(float lo, float hi) { return f2bf(lo) | (f2bf(hi) << 16); }
; __device__ __forceinline__ void tr_block(const float* src  , int ldw, bf16* dst  , int K, LAS float* scr, int lane) {
;     const int kr = lane >> 3, c4 = lane & 7;
;     f32x4 v[8];
; #pragma unroll
;     for (int i = 0; i < 8; ++i) v[i] = *(const f32x4*)(src + (size_t)(8 * i + kr) * ldw + 4 * c4);
; #pragma unroll
;     for (int i = 0; i < 8; ++i) { LAS float* d = scr + (8 * i + kr) * 33 + 4 * c4; d[0] = v[i].x; d[1] = v[i].y; d[2] = v[i].z; d[3] = v[i].w; }
;     asm volatile("s_waitcnt lgkmcnt(0)" ::: "memory");
;     const int c = lane & 7;
; #pragma unroll
;     for (int j = 0; j < 4; ++j) { const int n = (lane >> 3) + 8 * j; const LAS float* s = scr + (8 * c) * 33 + n;
;         v4u o; o.x = pk2(s[0 * 33], s[1 * 33]); o.y = pk2(s[2 * 33], s[3 * 33]); o.z = pk2(s[4 * 33], s[5 * 33]); o.w = pk2(s[6 * 33], s[7 * 33]);
;         *(v4u*)(dst + (size_t)n * K + 8 * c) = o; }
;     asm volatile("s_waitcnt lgkmcnt(0)" ::: "memory");
; template <int SEL> __global__ void __launch_bounds__(NWAVES * 64, 2) fwd_kernel(Args args) {
;     ...
;                 if (r < I_A) { tr_seg<0>(win, NIN, 1024, 0, 1536, wt, 0, 0, scr, r, lane); continue; } r -= I_A;
.LBB0_39:
	s_andn2_b64 vcc, exec, s[20:21]
	s_cbranch_vccnz .LBB0_9
	s_mul_hi_i32 s4, s54, 0x2aaaaaab
	s_lshr_b32 s18, s4, 31
	s_ashr_i32 s4, s4, 3
	s_add_i32 s4, s4, s18
	s_mul_i32 s18, s4, 48
	s_sub_i32 s19, s54, s18
	s_lshl_b32 s18, s4, 6
	s_lshl_b32 s20, s19, 5
	s_ashr_i32 s19, s18, 31
	s_mul_i32 s4, s4, 0x140800
	s_mul_hi_i32 s21, s18, 0x5020
	s_add_u32 s4, s55, s4
	s_addc_u32 s56, s56, s21
	s_ashr_i32 s21, s20, 31
	s_lshl_b64 s[54:55], s[20:21], 2
	s_add_u32 s54, s4, s54
	s_addc_u32 s55, s56, s55
	v_lshl_add_u64 v[92:93], s[54:55], 0, v[2:3]
	v_lshlrev_b32_e32 v64, 2, v34
	v_mov_b32_e32 v65, v3
	v_lshl_add_u64 v[88:89], v[92:93], 0, v[64:65]
	v_add_co_u32_e32 v68, vcc, s48, v88
	v_lshlrev_b32_e32 v72, 2, v38
	s_nop 0
	v_addc_co_u32_e32 v69, vcc, 0, v89, vcc
	v_add_co_u32_e32 v80, vcc, s49, v88
	v_mov_b32_e32 v73, v3
	s_nop 0
	v_addc_co_u32_e32 v81, vcc, 0, v89, vcc
	v_add_co_u32_e32 v84, vcc, s50, v88
	v_lshlrev_b32_e32 v74, 2, v40
	v_mov_b32_e32 v75, v3
	v_addc_co_u32_e32 v85, vcc, 0, v89, vcc
	v_lshl_add_u64 v[72:73], v[92:93], 0, v[72:73]
	v_lshl_add_u64 v[76:77], v[92:93], 0, v[74:75]
	global_load_dwordx4 v[64:67], v[88:89], off nt
	s_nop 0
	global_load_dwordx4 v[68:71], v[68:69], off offset:256
	s_nop 0
	global_load_dwordx4 v[72:75], v[72:73], off nt
	s_nop 0
	global_load_dwordx4 v[76:79], v[76:77], off nt
	s_nop 0
	global_load_dwordx4 v[80:83], v[80:81], off offset:512
	s_nop 0
	global_load_dwordx4 v[84:87], v[84:85], off offset:768
	v_add_co_u32_e32 v88, vcc, s51, v88
	v_lshlrev_b32_e32 v94, 2, v36
	s_nop 0
	v_addc_co_u32_e32 v89, vcc, 0, v89, vcc
	global_load_dwordx4 v[88:91], v[88:89], off offset:1024
	v_mov_b32_e32 v95, v3
	v_lshl_add_u64 v[92:93], v[92:93], 0, v[94:95]
	global_load_dwordx4 v[92:95], v[92:93], off nt
	v_add_u32_e32 v19, v13, v15
	v_add_u32_e32 v27, 0x420, v19
	v_add_u32_e32 v29, 0x428, v19
	v_add_u32_e32 v31, 0x840, v19
	v_add_u32_e32 v33, 0x848, v19
	v_add_u32_e32 v35, 0xc60, v19
	v_add_u32_e32 v37, 0xc68, v19
	v_add_u32_e32 v39, 0x1080, v19
	v_add_u32_e32 v41, 0x1088, v19
	v_add_u32_e32 v43, 0x14a0, v19
	v_add_u32_e32 v45, 0x14a8, v19
	v_add_u32_e32 v47, 0x18c0, v19
	v_add_u32_e32 v49, 0x18c8, v19
	v_add_u32_e32 v51, 0x1ce0, v19
	v_add_u32_e32 v53, 0x1ce8, v19
	s_lshl_b64 s[20:21], s[20:21], 11
	s_add_u32 s4, s52, s20
	s_addc_u32 s20, s53, s21
	s_lshl_b64 s[18:19], s[18:19], 1
	s_add_u32 s18, s4, s18
	v_lshlrev_b32_e32 v96, 1, v20
	v_mov_b32_e32 v97, v3
	s_addc_u32 s19, s20, s19
	s_waitcnt vmcnt(7)
	ds_write2_b32 v19, v64, v65 offset1:1
	ds_write2_b32 v19, v66, v67 offset0:2 offset1:3
	s_waitcnt vmcnt(5)
	ds_write2_b32 v47, v72, v73 offset1:1
	ds_write2_b32 v49, v74, v75 offset1:1
	s_waitcnt vmcnt(4)
	ds_write2_b32 v51, v76, v77 offset1:1
	ds_write2_b32 v53, v78, v79 offset1:1
	ds_write2_b32 v27, v68, v69 offset1:1
	ds_write2_b32 v29, v70, v71 offset1:1
	s_waitcnt vmcnt(3)
	ds_write2_b32 v31, v80, v81 offset1:1
	ds_write2_b32 v33, v82, v83 offset1:1
	s_waitcnt vmcnt(2)
	ds_write2_b32 v35, v84, v85 offset1:1
	ds_write2_b32 v37, v86, v87 offset1:1
	s_waitcnt vmcnt(1)
	ds_write2_b32 v39, v88, v89 offset1:1
	ds_write2_b32 v41, v90, v91 offset1:1
	s_waitcnt vmcnt(0)
	ds_write2_b32 v43, v92, v93 offset1:1
	ds_write2_b32 v45, v94, v95 offset1:1
	s_waitcnt lgkmcnt(0)
	ds_read2_b32 v[68:69], v17 offset1:8
	ds_read2_b32 v[70:71], v17 offset0:33 offset1:41
	ds_read2_b32 v[74:75], v17 offset0:66 offset1:74
	ds_read2_b32 v[76:77], v17 offset0:99 offset1:107
	ds_read2_b32 v[78:79], v17 offset0:132 offset1:140
	ds_read2_b32 v[80:81], v17 offset0:165 offset1:173
	s_waitcnt lgkmcnt(5)
	v_bfe_u32 v19, v68, 16, 1
	s_waitcnt lgkmcnt(4)
	v_bfe_u32 v27, v70, 16, 1
	v_add3_u32 v19, v68, v19, s46
	v_add3_u32 v27, v70, v27, s46
	v_lshrrev_b32_e32 v19, 16, v19
	v_and_or_b32 v64, v27, s47, v19
	s_waitcnt lgkmcnt(3)
	v_bfe_u32 v19, v74, 16, 1
	v_add3_u32 v19, v74, v19, s46
	s_waitcnt lgkmcnt(2)
	v_bfe_u32 v27, v76, 16, 1
	ds_read2_b32 v[82:83], v17 offset0:198 offset1:206
	v_lshrrev_b32_e32 v19, 16, v19
	v_add3_u32 v27, v76, v27, s46
	ds_read2_b32 v[84:85], v17 offset0:231 offset1:239
	v_and_or_b32 v65, v27, s47, v19
	s_waitcnt lgkmcnt(3)
; #define LAS __attribute__((address_space(3)))
; __device__ __forceinline__ unsigned pk2(float lo, float hi) { return f2bf(lo) | (f2bf(hi) << 16); }
; __device__ __forceinline__ void tr_block(const float* src  , int ldw, bf16* dst  , int K, LAS float* scr, int lane) {
;     ...
;     const int c = lane & 7;
; #pragma unroll
;     for (int j = 0; j < 4; ++j) { const int n = (lane >> 3) + 8 * j; const LAS float* s = scr + (8 * c) * 33 + n;
;         v4u o; o.x = pk2(s[0 * 33], s[1 * 33]); o.y = pk2(s[2 * 33], s[3 * 33]); o.z = pk2(s[4 * 33], s[5 * 33]); o.w = pk2(s[6 * 33], s[7 * 33]);
;         *(v4u*)(dst + (size_t)n * K + 8 * c) = o; }
;     asm volatile("s_waitcnt lgkmcnt(0)" ::: "memory");
; template <int SEL> __global__ void __launch_bounds__(NWAVES * 64, 2) fwd_kernel(Args args) {
;     ...
;         for (int it = gw; it < NITEMS; it += NGW) {
	v_bfe_u32 v19, v78, 16, 1
	v_add3_u32 v19, v78, v19, s46
	s_waitcnt lgkmcnt(2)
	v_bfe_u32 v27, v80, 16, 1
	v_lshrrev_b32_e32 v19, 16, v19
	v_add3_u32 v27, v80, v27, s46
	v_and_or_b32 v66, v27, s47, v19
	s_waitcnt lgkmcnt(1)
	v_bfe_u32 v19, v82, 16, 1
	v_add3_u32 v19, v82, v19, s46
	s_waitcnt lgkmcnt(0)
	v_bfe_u32 v27, v84, 16, 1
	v_lshrrev_b32_e32 v19, 16, v19
	v_add3_u32 v27, v84, v27, s46
	v_and_or_b32 v67, v27, s47, v19
	v_bfe_u32 v19, v69, 16, 1
	v_lshl_add_u64 v[72:73], s[18:19], 0, v[96:97]
	v_lshlrev_b32_e32 v86, 1, v4
	v_mov_b32_e32 v87, v3
	v_add3_u32 v19, v69, v19, s46
	v_bfe_u32 v27, v71, 16, 1
	v_lshl_add_u64 v[86:87], v[72:73], 0, v[86:87]
	v_lshrrev_b32_e32 v19, 16, v19
	v_add3_u32 v27, v71, v27, s46
	global_store_dwordx4 v[86:87], v[64:67], off nt
	v_lshlrev_b32_e32 v68, 1, v6
	v_mov_b32_e32 v69, v3
	v_and_or_b32 v64, v27, s47, v19
	v_bfe_u32 v19, v75, 16, 1
	v_add3_u32 v19, v75, v19, s46
	v_bfe_u32 v27, v77, 16, 1
	v_lshrrev_b32_e32 v19, 16, v19
	v_add3_u32 v27, v77, v27, s46
	v_and_or_b32 v65, v27, s47, v19
	v_bfe_u32 v19, v79, 16, 1
	v_add3_u32 v19, v79, v19, s46
	v_bfe_u32 v27, v81, 16, 1
	v_lshrrev_b32_e32 v19, 16, v19
	v_add3_u32 v27, v81, v27, s46
	v_and_or_b32 v66, v27, s47, v19
	v_bfe_u32 v19, v83, 16, 1
	v_add3_u32 v19, v83, v19, s46
	v_bfe_u32 v27, v85, 16, 1
	v_lshrrev_b32_e32 v19, 16, v19
	v_add3_u32 v27, v85, v27, s46
	v_and_or_b32 v67, v27, s47, v19
	ds_read2_b32 v[70:71], v17 offset0:16 offset1:24
	v_lshl_add_u64 v[68:69], v[72:73], 0, v[68:69]
	global_store_dwordx4 v[68:69], v[64:67], off nt
	ds_read2_b32 v[68:69], v17 offset0:49 offset1:57
	ds_read2_b32 v[74:75], v17 offset0:82 offset1:90
	ds_read2_b32 v[76:77], v17 offset0:115 offset1:123
	s_waitcnt lgkmcnt(3)
	v_bfe_u32 v19, v70, 16, 1
	v_add3_u32 v19, v70, v19, s46
	s_waitcnt lgkmcnt(2)
	v_bfe_u32 v27, v68, 16, 1
	ds_read2_b32 v[78:79], v17 offset0:148 offset1:156
	v_lshrrev_b32_e32 v19, 16, v19
	v_add3_u32 v27, v68, v27, s46
	ds_read2_b32 v[80:81], v17 offset0:181 offset1:189
	v_and_or_b32 v64, v27, s47, v19
	s_waitcnt lgkmcnt(3)
	v_bfe_u32 v19, v74, 16, 1
	v_add3_u32 v19, v74, v19, s46
	s_waitcnt lgkmcnt(2)
	v_bfe_u32 v27, v76, 16, 1
	ds_read2_b32 v[82:83], v17 offset0:214 offset1:222
	v_lshrrev_b32_e32 v19, 16, v19
	v_add3_u32 v27, v76, v27, s46
	ds_read2_b32 v[84:85], v17 offset0:247 offset1:255
	v_and_or_b32 v65, v27, s47, v19
	s_waitcnt lgkmcnt(3)
	v_bfe_u32 v19, v78, 16, 1
	v_add3_u32 v19, v78, v19, s46
	s_waitcnt lgkmcnt(2)
	v_bfe_u32 v27, v80, 16, 1
	v_lshrrev_b32_e32 v19, 16, v19
	v_add3_u32 v27, v80, v27, s46
	v_and_or_b32 v66, v27, s47, v19
	s_waitcnt lgkmcnt(1)
	v_bfe_u32 v19, v82, 16, 1
	v_add3_u32 v19, v82, v19, s46
	s_waitcnt lgkmcnt(0)
	v_bfe_u32 v27, v84, 16, 1
	v_lshrrev_b32_e32 v19, 16, v19
	v_add3_u32 v27, v84, v27, s46
	v_and_or_b32 v67, v27, s47, v19
	v_bfe_u32 v19, v71, 16, 1
	v_lshlrev_b32_e32 v86, 1, v8
	v_mov_b32_e32 v87, v3
	v_add3_u32 v19, v71, v19, s46
	v_bfe_u32 v27, v69, 16, 1
	v_lshl_add_u64 v[86:87], v[72:73], 0, v[86:87]
	v_lshrrev_b32_e32 v19, 16, v19
	v_add3_u32 v27, v69, v27, s46
	global_store_dwordx4 v[86:87], v[64:67], off nt
	v_lshlrev_b32_e32 v68, 1, v10
	v_mov_b32_e32 v69, v3
	v_and_or_b32 v64, v27, s47, v19
	v_bfe_u32 v19, v75, 16, 1
	v_add3_u32 v19, v75, v19, s46
	v_bfe_u32 v27, v77, 16, 1
	v_lshrrev_b32_e32 v19, 16, v19
	v_add3_u32 v27, v77, v27, s46
	v_and_or_b32 v65, v27, s47, v19
	v_bfe_u32 v19, v79, 16, 1
	v_add3_u32 v19, v79, v19, s46
	v_bfe_u32 v27, v81, 16, 1
	v_lshrrev_b32_e32 v19, 16, v19
	v_add3_u32 v27, v81, v27, s46
	v_and_or_b32 v66, v27, s47, v19
	v_bfe_u32 v19, v83, 16, 1
	v_add3_u32 v19, v83, v19, s46
	v_bfe_u32 v27, v85, 16, 1
	v_lshrrev_b32_e32 v19, 16, v19
	v_add3_u32 v27, v85, v27, s46
	v_and_or_b32 v67, v27, s47, v19
	v_lshl_add_u64 v[68:69], v[72:73], 0, v[68:69]
	global_store_dwordx4 v[68:69], v[64:67], off nt
	s_waitcnt lgkmcnt(0)
	s_branch .LBB0_9
